# attention softmax in place in the QK accumulators: 4 packed adds replace 8 subs, ones-operand rebuild moves removed where nothing clobbers v37..39
# speedup vs baseline: 1.0090x; 1.0023x over previous
.LBB0_348:
	v_pk_add_f32 v[136:137], v[136:137], v[168:169] op_sel:[0,1] op_sel_hi:[1,1] neg_lo:[0,1] neg_hi:[0,1]
	v_pk_add_f32 v[138:139], v[138:139], v[168:169] op_sel:[0,1] op_sel_hi:[1,1] neg_lo:[0,1] neg_hi:[0,1]
	v_pk_add_f32 v[140:141], v[140:141], v[168:169] op_sel:[0,1] op_sel_hi:[1,1] neg_lo:[0,1] neg_hi:[0,1]
	v_pk_add_f32 v[142:143], v[142:143], v[168:169] op_sel:[0,1] op_sel_hi:[1,1] neg_lo:[0,1] neg_hi:[0,1]
	v_exp_f32_e32 v136, v136
	v_exp_f32_e32 v137, v137
	v_exp_f32_e32 v138, v138
	v_exp_f32_e32 v139, v139
	v_exp_f32_e32 v140, v140
	v_exp_f32_e32 v141, v141
	v_exp_f32_e32 v142, v142
	v_exp_f32_e32 v143, v143
	v_mov_b32_e32 v37, v36
	v_mov_b32_e32 v38, v36
	v_mov_b32_e32 v39, v36
	v_cvt_pk_bf16_f32 v136, v136, v137
	v_cvt_pk_bf16_f32 v137, v138, v139
	v_cvt_pk_bf16_f32 v138, v140, v141
	v_cvt_pk_bf16_f32 v139, v142, v143
	s_nop 1
	v_mfma_f32_16x16x32_bf16 v[52:55], v[120:123], v[136:139], v[52:55]
	v_mfma_f32_16x16x32_bf16 v[48:51], v[124:127], v[136:139], v[48:51]
	v_mfma_f32_16x16x32_bf16 v[44:47], v[128:131], v[136:139], v[44:47]
	v_mfma_f32_16x16x32_bf16 v[40:43], v[132:135], v[136:139], v[40:43]
	v_mfma_f32_16x16x32_bf16 v[56:59], v[36:39], v[136:139], v[56:59]
	s_add_u32 s34, s34, 0x10000
	s_addc_u32 s35, s35, 0
	s_add_i32 s30, s30, 2
	s_cmp_lg_u32 s34, 0x80000
	v_add_u32_e32 v212, 0x7c, v212
	s_cbranch_scc0 .LBB0_361
.LBB0_349:
	v_lshl_add_u64 v[34:35], v[152:153], 0, s[34:35]
	s_mov_b32 s0, 0x11708000
	v_add_co_u32_e32 v120, vcc, s0, v34
	s_mov_b32 s0, 0x1170c000
	s_nop 0
	v_addc_co_u32_e32 v121, vcc, 0, v35, vcc
	v_add_co_u32_e32 v34, vcc, s0, v34
	v_lshl_add_u64 v[38:39], v[154:155], 0, s[34:35]
	s_nop 0
	v_addc_co_u32_e32 v35, vcc, 0, v35, vcc
	global_load_dwordx4 v[136:139], v[120:121], off
	global_load_dwordx4 v[140:143], v[120:121], off offset:1024
	global_load_dwordx4 v[148:151], v[34:35], off
	global_load_dwordx4 v[144:147], v[34:35], off offset:1024
	s_nop 0
	global_load_dwordx4 v[120:123], v[38:39], off offset:-2048
	global_load_dwordx4 v[124:127], v[38:39], off offset:-1024
	global_load_dwordx4 v[128:131], v[38:39], off
	global_load_dwordx4 v[132:135], v[38:39], off offset:1024
	ds_read_b128 v[214:217], v168 offset:20480
	ds_read_b128 v[218:221], v168 offset:21504
	ds_read_b32 v222, v212 offset:128
	ds_read_b32 v246, v212 offset:192
	ds_read_b32 v223, v212 offset:132
	ds_read_b32 v247, v212 offset:196
	ds_read_b32 v224, v212 offset:136
	ds_read_b32 v248, v212 offset:200
	ds_read_b32 v225, v212 offset:140
	ds_read_b32 v249, v212 offset:204
	s_waitcnt vmcnt(15) lgkmcnt(1)
	v_mfma_f32_16x16x32_bf16 v[222:225], v[24:27], v[214:217], v[222:225]
	s_waitcnt vmcnt(13) lgkmcnt(0)
	v_mfma_f32_16x16x32_bf16 v[214:217], v[28:31], v[214:217], v[246:249]
	v_mfma_f32_16x16x32_bf16 v[222:225], v[16:19], v[218:221], v[222:225]
	s_waitcnt vmcnt(12)
	v_mfma_f32_16x16x32_bf16 v[216:219], v[20:23], v[218:221], v[214:217]
	s_nop 5
	v_cndmask_b32_e64 v222, v242, v222, s[42:43]
	v_cndmask_b32_e64 v223, v242, v223, s[46:47]
	v_cndmask_b32_e64 v224, v242, v224, s[48:49]
	v_cndmask_b32_e64 v225, v242, v225, s[50:51]
	v_cndmask_b32_e64 v216, v242, v216, s[44:45]
	v_cndmask_b32_e64 v217, v242, v217, s[52:53]
	v_cndmask_b32_e64 v218, v242, v218, s[54:55]
	v_cndmask_b32_e64 v219, v242, v219, s[56:57]
	v_max3_f32 v215, v222, v223, v224
	v_max3_f32 v213, v225, v216, v217
	v_max3_f32 v215, v215, v218, v219
	v_max_f32_e32 v215, v215, v213
	v_add_f32_e32 v214, 0x41000000, v170
	v_cmp_gt_f32_e32 vcc, v215, v214
	s_cbranch_vccz .LBB0_351
	v_mov_b32_e32 v214, v215
	s_nop 1
	v_permlane16_swap_b32 v215, v214
	s_nop 0
	v_max_f32_e32 v214, v214, v214
	v_max_f32_e32 v215, v215, v215
	v_max_f32_e32 v215, v215, v214
	v_mov_b32_e32 v214, v215
	s_nop 1
	v_permlane32_swap_b32 v214, v215
	s_nop 0
	v_max3_f32 v215, v170, v214, v215
	v_sub_f32_e32 v170, v170, v215
	v_exp_f32_e32 v170, v170
	s_nop 0
	v_pk_mul_f32 v[74:75], v[74:75], v[170:171] op_sel_hi:[1,0]
	v_pk_mul_f32 v[72:73], v[72:73], v[170:171] op_sel_hi:[1,0]
	v_pk_mul_f32 v[70:71], v[70:71], v[170:171] op_sel_hi:[1,0]
	v_pk_mul_f32 v[68:69], v[68:69], v[170:171] op_sel_hi:[1,0]
	v_pk_mul_f32 v[66:67], v[66:67], v[170:171] op_sel_hi:[1,0]
	v_pk_mul_f32 v[64:65], v[64:65], v[170:171] op_sel_hi:[1,0]
	v_pk_mul_f32 v[62:63], v[62:63], v[170:171] op_sel_hi:[1,0]
	v_pk_mul_f32 v[60:61], v[60:61], v[170:171] op_sel_hi:[1,0]
	v_pk_mul_f32 v[78:79], v[78:79], v[170:171] op_sel_hi:[1,0]
	v_pk_mul_f32 v[76:77], v[76:77], v[170:171] op_sel_hi:[1,0]
	v_mov_b32_e32 v170, v215
.LBB0_351:
	v_pk_add_f32 v[222:223], v[222:223], v[170:171] op_sel_hi:[1,0] neg_lo:[0,1] neg_hi:[0,1]
	v_pk_add_f32 v[224:225], v[224:225], v[170:171] op_sel_hi:[1,0] neg_lo:[0,1] neg_hi:[0,1]
	v_pk_add_f32 v[216:217], v[216:217], v[170:171] op_sel_hi:[1,0] neg_lo:[0,1] neg_hi:[0,1]
	v_pk_add_f32 v[218:219], v[218:219], v[170:171] op_sel_hi:[1,0] neg_lo:[0,1] neg_hi:[0,1]
	v_exp_f32_e32 v222, v222
	v_exp_f32_e32 v223, v223
	v_exp_f32_e32 v224, v224
	v_exp_f32_e32 v225, v225
	v_exp_f32_e32 v216, v216
	v_exp_f32_e32 v217, v217
	v_exp_f32_e32 v218, v218
	v_exp_f32_e32 v219, v219
	v_mov_b32_e32 v37, v36
	v_mov_b32_e32 v38, v36
	v_mov_b32_e32 v39, v36
	v_cvt_pk_bf16_f32 v214, v222, v223
	v_cvt_pk_bf16_f32 v215, v224, v225
	v_cvt_pk_bf16_f32 v216, v216, v217
	v_cvt_pk_bf16_f32 v217, v218, v219
	s_waitcnt vmcnt(11)
	s_nop 0
	v_mfma_f32_16x16x32_bf16 v[72:75], v[0:3], v[214:217], v[72:75]
	s_waitcnt vmcnt(10)
	v_mfma_f32_16x16x32_bf16 v[68:71], v[4:7], v[214:217], v[68:71]
	s_waitcnt vmcnt(9)
	v_mfma_f32_16x16x32_bf16 v[64:67], v[8:11], v[214:217], v[64:67]
	s_waitcnt vmcnt(8)
	v_mfma_f32_16x16x32_bf16 v[60:63], v[12:15], v[214:217], v[60:63]
	v_mfma_f32_16x16x32_bf16 v[76:79], v[36:39], v[214:217], v[76:79]
	ds_read_b128 v[214:217], v168 offset:22528
	ds_read_b128 v[218:221], v168 offset:23552
	ds_read_b32 v222, v212 offset:64
	ds_read_b32 v246, v212 offset:128
	ds_read_b32 v223, v212 offset:68
	ds_read_b32 v247, v212 offset:132
	ds_read_b32 v224, v212 offset:72
	ds_read_b32 v248, v212 offset:136
	ds_read_b32 v225, v212 offset:76
	ds_read_b32 v249, v212 offset:140
	s_waitcnt lgkmcnt(1)
	v_mfma_f32_16x16x32_bf16 v[222:225], v[24:27], v[214:217], v[222:225]
	s_waitcnt lgkmcnt(0)
	v_mfma_f32_16x16x32_bf16 v[214:217], v[28:31], v[214:217], v[246:249]
	v_mfma_f32_16x16x32_bf16 v[214:217], v[20:23], v[218:221], v[214:217]
	v_mfma_f32_16x16x32_bf16 v[222:225], v[16:19], v[218:221], v[222:225]
	s_nop 5
	s_nop 0
	v_bfi_b32 v214, v173, v214, s29
	v_bfi_b32 v215, v174, v215, s29
	v_bfi_b32 v222, v156, v222, s29
	v_bfi_b32 v223, v157, v223, s29
	v_bfi_b32 v216, v175, v216, s29
	v_bfi_b32 v224, v158, v224, s29
	v_bfi_b32 v225, v159, v225, s29
	v_bfi_b32 v217, v176, v217, s29
	v_max3_f32 v218, v214, v215, v222
	v_max3_f32 v220, v223, v216, v224
	v_max3_f32 v218, v218, v225, v217
	v_max_f32_e32 v218, v218, v220
	v_add_f32_e32 v219, 0x41000000, v172
	v_cmp_gt_f32_e32 vcc, v218, v219
	s_cbranch_vccz .LBB0_353
	v_mov_b32_e32 v219, v218
	s_nop 1
	v_permlane16_swap_b32 v218, v219
	s_nop 0
	v_max_f32_e32 v219, v219, v219
	v_max_f32_e32 v218, v218, v218
	v_max_f32_e32 v218, v218, v219
	v_mov_b32_e32 v219, v218
	s_nop 1
	v_permlane32_swap_b32 v218, v219
	s_nop 0
	v_max3_f32 v218, v172, v218, v219
	v_sub_f32_e32 v172, v172, v218
	v_exp_f32_e32 v172, v172
	s_nop 0
	v_pk_mul_f32 v[114:115], v[114:115], v[172:173] op_sel_hi:[1,0]
	v_pk_mul_f32 v[112:113], v[112:113], v[172:173] op_sel_hi:[1,0]
	v_pk_mul_f32 v[110:111], v[110:111], v[172:173] op_sel_hi:[1,0]
	v_pk_mul_f32 v[108:109], v[108:109], v[172:173] op_sel_hi:[1,0]
	v_pk_mul_f32 v[106:107], v[106:107], v[172:173] op_sel_hi:[1,0]
	v_pk_mul_f32 v[104:105], v[104:105], v[172:173] op_sel_hi:[1,0]
	v_pk_mul_f32 v[102:103], v[102:103], v[172:173] op_sel_hi:[1,0]
	v_pk_mul_f32 v[100:101], v[100:101], v[172:173] op_sel_hi:[1,0]
	v_pk_mul_f32 v[118:119], v[118:119], v[172:173] op_sel_hi:[1,0]
	v_pk_mul_f32 v[116:117], v[116:117], v[172:173] op_sel_hi:[1,0]
	v_mov_b32_e32 v172, v218
.LBB0_353:
	v_pk_add_f32 v[216:217], v[216:217], v[172:173] op_sel_hi:[1,0] neg_lo:[0,1] neg_hi:[0,1]
	v_pk_add_f32 v[214:215], v[214:215], v[172:173] op_sel_hi:[1,0] neg_lo:[0,1] neg_hi:[0,1]
	v_pk_add_f32 v[222:223], v[222:223], v[172:173] op_sel_hi:[1,0] neg_lo:[0,1] neg_hi:[0,1]
	v_pk_add_f32 v[224:225], v[224:225], v[172:173] op_sel_hi:[1,0] neg_lo:[0,1] neg_hi:[0,1]
	v_exp_f32_e32 v216, v216
	v_exp_f32_e32 v217, v217
	v_exp_f32_e32 v214, v214
	v_exp_f32_e32 v215, v215
	v_exp_f32_e32 v222, v222
	v_exp_f32_e32 v223, v223
	v_exp_f32_e32 v224, v224
	v_exp_f32_e32 v225, v225
	v_cvt_pk_bf16_f32 v217, v216, v217
	v_cvt_pk_bf16_f32 v216, v214, v215
	v_cvt_pk_bf16_f32 v214, v222, v223
	v_cvt_pk_bf16_f32 v215, v224, v225
	s_nop 1
	v_mfma_f32_16x16x32_bf16 v[112:115], v[0:3], v[214:217], v[112:115]
	v_mfma_f32_16x16x32_bf16 v[108:111], v[4:7], v[214:217], v[108:111]
	v_mfma_f32_16x16x32_bf16 v[104:107], v[8:11], v[214:217], v[104:107]
	v_mfma_f32_16x16x32_bf16 v[100:103], v[12:15], v[214:217], v[100:103]
	v_mfma_f32_16x16x32_bf16 v[116:119], v[36:39], v[214:217], v[116:119]
	ds_read_b128 v[214:217], v168 offset:24576
	ds_read_b128 v[218:221], v168 offset:25600
	ds_read_b32 v222, v212
	ds_read_b32 v246, v212 offset:64
	ds_read_b32 v223, v212 offset:4
	ds_read_b32 v247, v212 offset:68
	ds_read_b32 v224, v212 offset:8
	ds_read_b32 v248, v212 offset:72
	ds_read_b32 v225, v212 offset:12
	ds_read_b32 v249, v212 offset:76
	s_waitcnt lgkmcnt(1)
	v_mfma_f32_16x16x32_bf16 v[24:27], v[24:27], v[214:217], v[222:225]
	v_mfma_f32_16x16x32_bf16 v[16:19], v[16:19], v[218:221], v[24:27]
	s_waitcnt lgkmcnt(0)
	s_nop 5
	v_mfma_f32_16x16x32_bf16 v[24:27], v[28:31], v[214:217], v[246:249]
	v_mfma_f32_16x16x32_bf16 v[20:23], v[20:23], v[218:221], v[24:27]
	s_nop 4
	v_cndmask_b32_e64 v16, v242, v16, s[58:59]
	s_nop 0
	v_bfi_b32 v17, v177, v17, s29
	v_bfi_b32 v18, v178, v18, s29
	v_bfi_b32 v19, v183, v19, s29
	v_bfi_b32 v20, v184, v20, s29
	v_bfi_b32 v21, v185, v21, s29
	v_bfi_b32 v22, v186, v22, s29
	v_bfi_b32 v23, v187, v23, s29
	v_max3_f32 v24, v16, v17, v18
	v_max3_f32 v26, v19, v20, v21
	v_max3_f32 v24, v24, v22, v23
	v_max_f32_e32 v24, v24, v26
	v_add_f32_e32 v25, 0x41000000, v171
	v_cmp_gt_f32_e32 vcc, v24, v25
	s_cbranch_vccz .LBB0_355
	v_mov_b32_e32 v25, v24
	s_nop 1
	v_permlane16_swap_b32 v24, v25
	s_nop 0
	v_max_f32_e32 v25, v25, v25
	v_max_f32_e32 v24, v24, v24
	v_max_f32_e32 v24, v24, v25
	v_mov_b32_e32 v25, v24
	s_nop 1
	v_permlane32_swap_b32 v24, v25
	s_nop 0
	v_max3_f32 v25, v171, v24, v25
	v_sub_f32_e32 v24, v171, v25
	v_exp_f32_e32 v24, v24
	v_mov_b32_e32 v171, v25
	v_pk_mul_f32 v[94:95], v[94:95], v[24:25] op_sel_hi:[1,0]
	v_pk_mul_f32 v[92:93], v[92:93], v[24:25] op_sel_hi:[1,0]
	v_pk_mul_f32 v[90:91], v[90:91], v[24:25] op_sel_hi:[1,0]
	v_pk_mul_f32 v[88:89], v[88:89], v[24:25] op_sel_hi:[1,0]
	v_pk_mul_f32 v[86:87], v[86:87], v[24:25] op_sel_hi:[1,0]
	v_pk_mul_f32 v[84:85], v[84:85], v[24:25] op_sel_hi:[1,0]
	v_pk_mul_f32 v[82:83], v[82:83], v[24:25] op_sel_hi:[1,0]
	v_pk_mul_f32 v[80:81], v[80:81], v[24:25] op_sel_hi:[1,0]
	v_pk_mul_f32 v[98:99], v[98:99], v[24:25] op_sel_hi:[1,0]
	v_pk_mul_f32 v[96:97], v[96:97], v[24:25] op_sel_hi:[1,0]
.LBB0_355:
	v_pk_add_f32 v[16:17], v[16:17], v[170:171] op_sel:[0,1] op_sel_hi:[1,1] neg_lo:[0,1] neg_hi:[0,1]
	v_pk_add_f32 v[18:19], v[18:19], v[170:171] op_sel:[0,1] op_sel_hi:[1,1] neg_lo:[0,1] neg_hi:[0,1]
	v_pk_add_f32 v[20:21], v[20:21], v[170:171] op_sel:[0,1] op_sel_hi:[1,1] neg_lo:[0,1] neg_hi:[0,1]
	v_pk_add_f32 v[22:23], v[22:23], v[170:171] op_sel:[0,1] op_sel_hi:[1,1] neg_lo:[0,1] neg_hi:[0,1]
	v_exp_f32_e32 v16, v16
	v_exp_f32_e32 v17, v17
	v_exp_f32_e32 v18, v18
	v_exp_f32_e32 v19, v19
	v_exp_f32_e32 v20, v20
	v_exp_f32_e32 v21, v21
	v_exp_f32_e32 v22, v22
	v_exp_f32_e32 v23, v23
	v_cvt_pk_bf16_f32 v16, v16, v17
	v_cvt_pk_bf16_f32 v17, v18, v19
	v_cvt_pk_bf16_f32 v18, v20, v21
	v_cvt_pk_bf16_f32 v19, v22, v23
	s_nop 1
	v_mfma_f32_16x16x32_bf16 v[92:95], v[0:3], v[16:19], v[92:95]
	v_mfma_f32_16x16x32_bf16 v[88:91], v[4:7], v[16:19], v[88:91]
	v_mfma_f32_16x16x32_bf16 v[84:87], v[8:11], v[16:19], v[84:87]
	v_mfma_f32_16x16x32_bf16 v[80:83], v[12:15], v[16:19], v[80:83]
	v_mfma_f32_16x16x32_bf16 v[96:99], v[36:39], v[16:19], v[96:99]
	s_cmp_eq_u32 s34, 0x70000
	s_cselect_b32 s40, s60, s30
	s_lshl_b32 s0, s40, 1
	s_lshl_b64 s[60:61], s[0:1], 14
	v_lshl_add_u64 v[0:1], v[164:165], 0, s[60:61]
	s_mov_b32 s41, s1
	s_lshl_b64 s[40:41], s[40:41], 15
	global_load_dwordx4 v[24:27], v[0:1], off
	global_load_dwordx4 v[16:19], v[0:1], off offset:1024
	v_add_co_u32_e32 v0, vcc, s72, v0
	v_lshl_add_u64 v[12:13], v[166:167], 0, s[40:41]
	s_nop 0
	v_addc_co_u32_e32 v1, vcc, 0, v1, vcc
	global_load_dwordx4 v[28:31], v[0:1], off
	global_load_dwordx4 v[20:23], v[0:1], off offset:1024
	s_nop 0
	global_load_dwordx4 v[0:3], v[12:13], off
	global_load_dwordx4 v[4:7], v[12:13], off offset:1024
	global_load_dwordx4 v[8:11], v[12:13], off offset:2048
	s_nop 0
	global_load_dwordx4 v[12:15], v[12:13], off offset:3072
	ds_read_b128 v[214:217], v168 offset:22528
	ds_read_b128 v[218:221], v168 offset:23552
	ds_read_b32 v222, v212 offset:192
	ds_read_b32 v246, v212 offset:256
	ds_read_b32 v223, v212 offset:196
	ds_read_b32 v247, v212 offset:260
	ds_read_b32 v224, v212 offset:200
	ds_read_b32 v248, v212 offset:264
	ds_read_b32 v225, v212 offset:204
	ds_read_b32 v249, v212 offset:268
	s_waitcnt vmcnt(15) lgkmcnt(1)
	v_mfma_f32_16x16x32_bf16 v[222:225], v[136:139], v[214:217], v[222:225]
	s_waitcnt vmcnt(13) lgkmcnt(0)
	v_mfma_f32_16x16x32_bf16 v[214:217], v[148:151], v[214:217], v[246:249]
	s_waitcnt vmcnt(12)
	v_mfma_f32_16x16x32_bf16 v[214:217], v[144:147], v[218:221], v[214:217]
	v_mfma_f32_16x16x32_bf16 v[222:225], v[140:143], v[218:221], v[222:225]
	s_nop 5
	s_nop 0
	v_bfi_b32 v214, v192, v214, s29
	v_bfi_b32 v215, v193, v215, s29
	v_bfi_b32 v222, v188, v222, s29
	v_bfi_b32 v223, v189, v223, s29
	v_bfi_b32 v216, v194, v216, s29
	v_bfi_b32 v224, v190, v224, s29
	v_bfi_b32 v225, v191, v225, s29
	v_bfi_b32 v217, v195, v217, s29
	v_max3_f32 v218, v214, v215, v222
	v_max3_f32 v220, v223, v216, v224
	v_max3_f32 v218, v218, v225, v217
	v_max_f32_e32 v218, v218, v220
	v_add_f32_e32 v219, 0x41000000, v172
	v_cmp_gt_f32_e32 vcc, v218, v219
	s_cbranch_vccz .LBB0_357
	v_mov_b32_e32 v219, v218
	s_nop 1
	v_permlane16_swap_b32 v218, v219
	s_nop 0
	v_max_f32_e32 v219, v219, v219
	v_max_f32_e32 v218, v218, v218
	v_max_f32_e32 v218, v218, v219
	v_mov_b32_e32 v219, v218
	s_nop 1
	v_permlane32_swap_b32 v219, v218
	s_nop 0
	v_max3_f32 v218, v172, v219, v218
	v_sub_f32_e32 v172, v172, v218
	v_exp_f32_e32 v172, v172
	s_nop 0
	v_pk_mul_f32 v[114:115], v[114:115], v[172:173] op_sel_hi:[1,0]
	v_pk_mul_f32 v[112:113], v[112:113], v[172:173] op_sel_hi:[1,0]
	v_pk_mul_f32 v[110:111], v[110:111], v[172:173] op_sel_hi:[1,0]
	v_pk_mul_f32 v[108:109], v[108:109], v[172:173] op_sel_hi:[1,0]
	v_pk_mul_f32 v[106:107], v[106:107], v[172:173] op_sel_hi:[1,0]
	v_pk_mul_f32 v[104:105], v[104:105], v[172:173] op_sel_hi:[1,0]
	v_pk_mul_f32 v[102:103], v[102:103], v[172:173] op_sel_hi:[1,0]
	v_pk_mul_f32 v[100:101], v[100:101], v[172:173] op_sel_hi:[1,0]
	v_pk_mul_f32 v[118:119], v[118:119], v[172:173] op_sel_hi:[1,0]
	v_pk_mul_f32 v[116:117], v[116:117], v[172:173] op_sel_hi:[1,0]
	v_mov_b32_e32 v172, v218
.LBB0_357:
	v_pk_add_f32 v[216:217], v[216:217], v[172:173] op_sel_hi:[1,0] neg_lo:[0,1] neg_hi:[0,1]
	v_pk_add_f32 v[214:215], v[214:215], v[172:173] op_sel_hi:[1,0] neg_lo:[0,1] neg_hi:[0,1]
	v_pk_add_f32 v[222:223], v[222:223], v[172:173] op_sel_hi:[1,0] neg_lo:[0,1] neg_hi:[0,1]
	v_pk_add_f32 v[224:225], v[224:225], v[172:173] op_sel_hi:[1,0] neg_lo:[0,1] neg_hi:[0,1]
	v_exp_f32_e32 v216, v216
	v_exp_f32_e32 v217, v217
	v_exp_f32_e32 v214, v214
	v_exp_f32_e32 v215, v215
	v_exp_f32_e32 v222, v222
	v_exp_f32_e32 v223, v223
	v_exp_f32_e32 v224, v224
	v_exp_f32_e32 v225, v225
	v_cvt_pk_bf16_f32 v217, v216, v217
	v_cvt_pk_bf16_f32 v216, v214, v215
	v_cvt_pk_bf16_f32 v214, v222, v223
	v_cvt_pk_bf16_f32 v215, v224, v225
	s_waitcnt vmcnt(11)
	s_nop 0
	v_mfma_f32_16x16x32_bf16 v[112:115], v[120:123], v[214:217], v[112:115]
	s_waitcnt vmcnt(10)
	v_mfma_f32_16x16x32_bf16 v[108:111], v[124:127], v[214:217], v[108:111]
	s_waitcnt vmcnt(9)
	v_mfma_f32_16x16x32_bf16 v[104:107], v[128:131], v[214:217], v[104:107]
	s_waitcnt vmcnt(8)
	v_mfma_f32_16x16x32_bf16 v[100:103], v[132:135], v[214:217], v[100:103]
	v_mfma_f32_16x16x32_bf16 v[116:119], v[36:39], v[214:217], v[116:119]
	ds_read_b128 v[214:217], v168 offset:24576
	ds_read_b128 v[218:221], v168 offset:25600
	ds_read_b32 v222, v212 offset:128
	ds_read_b32 v246, v212 offset:192
	ds_read_b32 v223, v212 offset:132
	ds_read_b32 v247, v212 offset:196
	ds_read_b32 v224, v212 offset:136
	ds_read_b32 v248, v212 offset:200
	ds_read_b32 v225, v212 offset:140
	ds_read_b32 v249, v212 offset:204
	s_waitcnt lgkmcnt(1)
	v_mfma_f32_16x16x32_bf16 v[222:225], v[136:139], v[214:217], v[222:225]
	s_waitcnt lgkmcnt(0)
	v_mfma_f32_16x16x32_bf16 v[214:217], v[148:151], v[214:217], v[246:249]
	v_readlane_b32 s60, v252, 47
	v_mfma_f32_16x16x32_bf16 v[222:225], v[140:143], v[218:221], v[222:225]
	v_mfma_f32_16x16x32_bf16 v[214:217], v[144:147], v[218:221], v[214:217]
	s_nop 6
	v_bfi_b32 v222, v196, v222, s29
	v_bfi_b32 v223, v197, v223, s29
	v_bfi_b32 v224, v198, v224, s29
	v_bfi_b32 v225, v199, v225, s29
	v_bfi_b32 v214, v200, v214, s29
	v_bfi_b32 v215, v201, v215, s29
	v_bfi_b32 v216, v202, v216, s29
	v_bfi_b32 v217, v203, v217, s29
	v_max3_f32 v32, v222, v223, v224
	v_max3_f32 v35, v225, v214, v215
	v_max3_f32 v32, v32, v216, v217
	v_max_f32_e32 v32, v32, v35
	v_add_f32_e32 v34, 0x41000000, v171
	v_cmp_gt_f32_e32 vcc, v32, v34
	s_cbranch_vccz .LBB0_359
	v_mov_b32_e32 v34, v32
	s_nop 1
	v_permlane16_swap_b32 v32, v34
	s_nop 0
	v_max_f32_e32 v34, v34, v34
	v_max_f32_e32 v32, v32, v32
	v_max_f32_e32 v32, v32, v34
	v_mov_b32_e32 v34, v32
	s_nop 1
	v_permlane32_swap_b32 v32, v34
	s_nop 0
	v_max3_f32 v32, v171, v32, v34
	v_sub_f32_e32 v171, v171, v32
	v_exp_f32_e32 v34, v171
	v_mov_b32_e32 v171, v32
	v_pk_mul_f32 v[94:95], v[94:95], v[34:35] op_sel_hi:[1,0]
	v_pk_mul_f32 v[92:93], v[92:93], v[34:35] op_sel_hi:[1,0]
	v_pk_mul_f32 v[90:91], v[90:91], v[34:35] op_sel_hi:[1,0]
	v_pk_mul_f32 v[88:89], v[88:89], v[34:35] op_sel_hi:[1,0]
	v_pk_mul_f32 v[86:87], v[86:87], v[34:35] op_sel_hi:[1,0]
	v_pk_mul_f32 v[84:85], v[84:85], v[34:35] op_sel_hi:[1,0]
	v_pk_mul_f32 v[82:83], v[82:83], v[34:35] op_sel_hi:[1,0]
	v_pk_mul_f32 v[80:81], v[80:81], v[34:35] op_sel_hi:[1,0]
	v_pk_mul_f32 v[98:99], v[98:99], v[34:35] op_sel_hi:[1,0]
	v_pk_mul_f32 v[96:97], v[96:97], v[34:35] op_sel_hi:[1,0]
.LBB0_359:
	v_pk_add_f32 v[216:217], v[216:217], v[170:171] op_sel:[0,1] op_sel_hi:[1,1] neg_lo:[0,1] neg_hi:[0,1]
	v_pk_add_f32 v[214:215], v[214:215], v[170:171] op_sel:[0,1] op_sel_hi:[1,1] neg_lo:[0,1] neg_hi:[0,1]
	v_pk_add_f32 v[222:223], v[222:223], v[170:171] op_sel:[0,1] op_sel_hi:[1,1] neg_lo:[0,1] neg_hi:[0,1]
	v_pk_add_f32 v[224:225], v[224:225], v[170:171] op_sel:[0,1] op_sel_hi:[1,1] neg_lo:[0,1] neg_hi:[0,1]
	v_exp_f32_e32 v216, v216
	v_exp_f32_e32 v217, v217
	v_exp_f32_e32 v214, v214
	v_exp_f32_e32 v215, v215
	v_exp_f32_e32 v222, v222
	v_exp_f32_e32 v223, v223
	v_exp_f32_e32 v224, v224
	v_exp_f32_e32 v225, v225
	v_cvt_pk_bf16_f32 v217, v216, v217
	v_cvt_pk_bf16_f32 v216, v214, v215
	v_cvt_pk_bf16_f32 v214, v222, v223
	v_cvt_pk_bf16_f32 v215, v224, v225
	s_nop 1
	v_mfma_f32_16x16x32_bf16 v[92:95], v[120:123], v[214:217], v[92:95]
	v_mfma_f32_16x16x32_bf16 v[88:91], v[124:127], v[214:217], v[88:91]
	v_mfma_f32_16x16x32_bf16 v[84:87], v[128:131], v[214:217], v[84:87]
	v_mfma_f32_16x16x32_bf16 v[80:83], v[132:135], v[214:217], v[80:83]
	v_mfma_f32_16x16x32_bf16 v[96:99], v[36:39], v[214:217], v[96:99]
	ds_read_b128 v[214:217], v168 offset:26624
	ds_read_b128 v[218:221], v168 offset:27648
	ds_read_b32 v222, v212 offset:64
	ds_read_b32 v246, v212 offset:128
	ds_read_b32 v223, v212 offset:68
	ds_read_b32 v247, v212 offset:132
	ds_read_b32 v224, v212 offset:72
	ds_read_b32 v248, v212 offset:136
	ds_read_b32 v225, v212 offset:76
	ds_read_b32 v249, v212 offset:140
	s_waitcnt lgkmcnt(1)
	v_mfma_f32_16x16x32_bf16 v[136:139], v[136:139], v[214:217], v[222:225]
	v_mfma_f32_16x16x32_bf16 v[136:139], v[140:143], v[218:221], v[136:139]
	s_waitcnt lgkmcnt(0)
	v_mfma_f32_16x16x32_bf16 v[140:143], v[148:151], v[214:217], v[246:249]
	v_mfma_f32_16x16x32_bf16 v[140:143], v[144:147], v[218:221], v[140:143]
	s_nop 4
	v_bfi_b32 v136, v204, v136, s29
	v_bfi_b32 v137, v205, v137, s29
	v_bfi_b32 v138, v206, v138, s29
	v_bfi_b32 v139, v207, v139, s29
	v_bfi_b32 v140, v208, v140, s29
	v_bfi_b32 v141, v209, v141, s29
	v_bfi_b32 v142, v210, v142, s29
	v_bfi_b32 v143, v211, v143, s29
	v_max3_f32 v32, v136, v137, v138
	v_max3_f32 v35, v139, v140, v141
	v_max3_f32 v32, v32, v142, v143
	v_max_f32_e32 v32, v32, v35
	v_add_f32_e32 v34, 0x41000000, v169
	v_cmp_gt_f32_e32 vcc, v32, v34
	s_cbranch_vccz .LBB0_348
	v_mov_b32_e32 v34, v32
	s_nop 1
	v_permlane16_swap_b32 v32, v34
	s_nop 0
	v_max_f32_e32 v34, v34, v34
	v_max_f32_e32 v32, v32, v32
	v_max_f32_e32 v32, v32, v34
	v_mov_b32_e32 v34, v32
	s_nop 1
	v_permlane32_swap_b32 v32, v34
	s_nop 0
	v_max3_f32 v32, v169, v32, v34
	v_sub_f32_e32 v34, v169, v32
	v_exp_f32_e32 v34, v34
	v_mov_b32_e32 v169, v32
	v_pk_mul_f32 v[54:55], v[54:55], v[34:35] op_sel_hi:[1,0]
	v_pk_mul_f32 v[52:53], v[52:53], v[34:35] op_sel_hi:[1,0]
	v_pk_mul_f32 v[50:51], v[50:51], v[34:35] op_sel_hi:[1,0]
	v_pk_mul_f32 v[48:49], v[48:49], v[34:35] op_sel_hi:[1,0]
	v_pk_mul_f32 v[46:47], v[46:47], v[34:35] op_sel_hi:[1,0]
	v_pk_mul_f32 v[44:45], v[44:45], v[34:35] op_sel_hi:[1,0]
	v_pk_mul_f32 v[42:43], v[42:43], v[34:35] op_sel_hi:[1,0]
	v_pk_mul_f32 v[40:41], v[40:41], v[34:35] op_sel_hi:[1,0]
	v_pk_mul_f32 v[58:59], v[58:59], v[34:35] op_sel_hi:[1,0]
	v_pk_mul_f32 v[56:57], v[56:57], v[34:35] op_sel_hi:[1,0]
	s_branch .LBB0_348

.LBB0_362:
	v_pk_add_f32 v[138:139], v[138:139], v[168:169] op_sel:[0,1] op_sel_hi:[1,1] neg_lo:[0,1] neg_hi:[0,1]
	v_pk_add_f32 v[136:137], v[136:137], v[168:169] op_sel:[0,1] op_sel_hi:[1,1] neg_lo:[0,1] neg_hi:[0,1]
	v_pk_add_f32 v[140:141], v[140:141], v[168:169] op_sel:[0,1] op_sel_hi:[1,1] neg_lo:[0,1] neg_hi:[0,1]
	v_pk_add_f32 v[142:143], v[142:143], v[168:169] op_sel:[0,1] op_sel_hi:[1,1] neg_lo:[0,1] neg_hi:[0,1]
	v_exp_f32_e32 v138, v138
	v_exp_f32_e32 v139, v139
	v_exp_f32_e32 v136, v136
	v_exp_f32_e32 v137, v137
	v_exp_f32_e32 v140, v140
	v_exp_f32_e32 v141, v141
	v_exp_f32_e32 v142, v142
	v_exp_f32_e32 v143, v143
	v_mov_b32_e32 v37, v36
	v_mov_b32_e32 v38, v36
	v_mov_b32_e32 v39, v36
	v_cvt_pk_bf16_f32 v139, v138, v139
	v_cvt_pk_bf16_f32 v138, v136, v137
	v_cvt_pk_bf16_f32 v136, v140, v141
	v_cvt_pk_bf16_f32 v137, v142, v143
	s_nop 1
	v_mfma_f32_16x16x32_bf16 v[52:55], v[120:123], v[136:139], v[52:55]
	v_mfma_f32_16x16x32_bf16 v[48:51], v[124:127], v[136:139], v[48:51]
	v_mfma_f32_16x16x32_bf16 v[44:47], v[128:131], v[136:139], v[44:47]
	v_mfma_f32_16x16x32_bf16 v[40:43], v[132:135], v[136:139], v[40:43]
	v_mfma_f32_16x16x32_bf16 v[56:59], v[36:39], v[136:139], v[56:59]
	s_add_i32 s30, s30, 2
	s_add_u32 s24, s24, 0x10000
	s_addc_u32 s25, s25, 0
	s_add_u32 s26, s26, 0x10000
	s_addc_u32 s27, s27, 0
	s_cmp_lt_u32 s31, 6
	s_cbranch_scc0 .LBB0_379

.LBB0_365:
	v_pk_add_f32 v[152:153], v[152:153], v[170:171] op_sel_hi:[1,0] neg_lo:[0,1] neg_hi:[0,1]
	v_pk_add_f32 v[154:155], v[154:155], v[170:171] op_sel_hi:[1,0] neg_lo:[0,1] neg_hi:[0,1]
	v_pk_add_f32 v[156:157], v[156:157], v[170:171] op_sel_hi:[1,0] neg_lo:[0,1] neg_hi:[0,1]
	v_pk_add_f32 v[158:159], v[158:159], v[170:171] op_sel_hi:[1,0] neg_lo:[0,1] neg_hi:[0,1]
	v_exp_f32_e32 v152, v152
	v_exp_f32_e32 v153, v153
	v_exp_f32_e32 v154, v154
	v_exp_f32_e32 v155, v155
	v_exp_f32_e32 v156, v156
	v_exp_f32_e32 v157, v157
	v_exp_f32_e32 v158, v158
	v_exp_f32_e32 v159, v159
	v_mov_b32_e32 v37, v36
	v_mov_b32_e32 v38, v36
	v_mov_b32_e32 v39, v36
	v_cvt_pk_bf16_f32 v152, v152, v153
	v_cvt_pk_bf16_f32 v153, v154, v155
	v_cvt_pk_bf16_f32 v154, v156, v157
	v_cvt_pk_bf16_f32 v155, v158, v159
	s_waitcnt vmcnt(11)
	s_nop 0
	v_mfma_f32_16x16x32_bf16 v[72:75], v[0:3], v[152:155], v[72:75]
	s_waitcnt vmcnt(10)
	v_mfma_f32_16x16x32_bf16 v[68:71], v[4:7], v[152:155], v[68:71]
	s_waitcnt vmcnt(9)
	v_mfma_f32_16x16x32_bf16 v[64:67], v[8:11], v[152:155], v[64:67]
	s_waitcnt vmcnt(8)
	v_mfma_f32_16x16x32_bf16 v[60:63], v[12:15], v[152:155], v[60:63]
	v_mfma_f32_16x16x32_bf16 v[76:79], v[36:39], v[152:155], v[76:79]
	ds_read_b128 v[152:155], v168 offset:22528
	ds_read_b128 v[174:177], v168 offset:23552
	s_waitcnt lgkmcnt(1)
	v_mfma_f32_16x16x32_bf16 v[156:159], v[24:27], v[152:155], 0
	v_mfma_f32_16x16x32_bf16 v[152:155], v[28:31], v[152:155], 0
	s_waitcnt lgkmcnt(0)
	v_mfma_f32_16x16x32_bf16 v[156:159], v[16:19], v[174:177], v[156:159]
	v_mfma_f32_16x16x32_bf16 v[152:155], v[20:23], v[174:177], v[152:155]
	s_nop 6
	v_max3_f32 v32, v156, v157, v158
	v_max3_f32 v35, v159, v152, v153
	v_max3_f32 v32, v32, v154, v155
	v_max_f32_e32 v32, v32, v35
	v_add_f32_e32 v34, 0x41000000, v172
	v_cmp_gt_f32_e32 vcc, v32, v34
	s_cbranch_vccz .LBB0_367
	v_mov_b32_e32 v34, v32
	s_nop 1
	v_permlane16_swap_b32 v32, v34
	s_nop 0
	v_max_f32_e32 v34, v34, v34
	v_max_f32_e32 v32, v32, v32
	v_max_f32_e32 v32, v32, v34
	v_mov_b32_e32 v34, v32
	s_nop 1
	v_permlane32_swap_b32 v32, v34
	s_nop 0
	v_max3_f32 v34, v172, v32, v34
	v_sub_f32_e32 v32, v172, v34
	v_exp_f32_e32 v32, v32
	v_mov_b32_e32 v172, v34
	v_pk_mul_f32 v[114:115], v[114:115], v[32:33] op_sel_hi:[1,0]
	v_pk_mul_f32 v[112:113], v[112:113], v[32:33] op_sel_hi:[1,0]
	v_pk_mul_f32 v[110:111], v[110:111], v[32:33] op_sel_hi:[1,0]
	v_pk_mul_f32 v[108:109], v[108:109], v[32:33] op_sel_hi:[1,0]
	v_pk_mul_f32 v[106:107], v[106:107], v[32:33] op_sel_hi:[1,0]
	v_pk_mul_f32 v[104:105], v[104:105], v[32:33] op_sel_hi:[1,0]
	v_pk_mul_f32 v[102:103], v[102:103], v[32:33] op_sel_hi:[1,0]
	v_pk_mul_f32 v[100:101], v[100:101], v[32:33] op_sel_hi:[1,0]
	v_pk_mul_f32 v[118:119], v[118:119], v[32:33] op_sel_hi:[1,0]
	v_pk_mul_f32 v[116:117], v[116:117], v[32:33] op_sel_hi:[1,0]
.LBB0_367:
	v_pk_add_f32 v[154:155], v[154:155], v[172:173] op_sel_hi:[1,0] neg_lo:[0,1] neg_hi:[0,1]
	v_pk_add_f32 v[152:153], v[152:153], v[172:173] op_sel_hi:[1,0] neg_lo:[0,1] neg_hi:[0,1]
	v_pk_add_f32 v[156:157], v[156:157], v[172:173] op_sel_hi:[1,0] neg_lo:[0,1] neg_hi:[0,1]
	v_pk_add_f32 v[158:159], v[158:159], v[172:173] op_sel_hi:[1,0] neg_lo:[0,1] neg_hi:[0,1]
	v_exp_f32_e32 v154, v154
	v_exp_f32_e32 v155, v155
	v_exp_f32_e32 v152, v152
	v_exp_f32_e32 v153, v153
	v_exp_f32_e32 v156, v156
	v_exp_f32_e32 v157, v157
	v_exp_f32_e32 v158, v158
	v_exp_f32_e32 v159, v159
	v_cvt_pk_bf16_f32 v155, v154, v155
	v_cvt_pk_bf16_f32 v154, v152, v153
	v_cvt_pk_bf16_f32 v152, v156, v157
	v_cvt_pk_bf16_f32 v153, v158, v159
	s_nop 1
	v_mfma_f32_16x16x32_bf16 v[112:115], v[0:3], v[152:155], v[112:115]
	v_mfma_f32_16x16x32_bf16 v[108:111], v[4:7], v[152:155], v[108:111]
	v_mfma_f32_16x16x32_bf16 v[104:107], v[8:11], v[152:155], v[104:107]
	v_mfma_f32_16x16x32_bf16 v[100:103], v[12:15], v[152:155], v[100:103]
	v_mfma_f32_16x16x32_bf16 v[116:119], v[36:39], v[152:155], v[116:119]
	ds_read_b128 v[152:155], v168 offset:24576
	ds_read_b128 v[174:177], v168 offset:25600
	s_waitcnt lgkmcnt(1)
	v_mfma_f32_16x16x32_bf16 v[156:159], v[24:27], v[152:155], 0
	v_mfma_f32_16x16x32_bf16 v[152:155], v[28:31], v[152:155], 0
	s_waitcnt lgkmcnt(0)
	v_mfma_f32_16x16x32_bf16 v[156:159], v[16:19], v[174:177], v[156:159]
	v_mfma_f32_16x16x32_bf16 v[152:155], v[20:23], v[174:177], v[152:155]
	s_nop 6
	v_max3_f32 v32, v156, v157, v158
	v_max3_f32 v35, v159, v152, v153
	v_max3_f32 v32, v32, v154, v155
	v_max_f32_e32 v32, v32, v35
	v_add_f32_e32 v34, 0x41000000, v171
	v_cmp_gt_f32_e32 vcc, v32, v34
	s_cbranch_vccz .LBB0_369
	v_mov_b32_e32 v34, v32
	s_nop 1
	v_permlane16_swap_b32 v32, v34
	s_nop 0
	v_max_f32_e32 v34, v34, v34
	v_max_f32_e32 v32, v32, v32
	v_max_f32_e32 v32, v32, v34
	v_mov_b32_e32 v34, v32
	s_nop 1
	v_permlane32_swap_b32 v34, v32
	s_nop 0
	v_max3_f32 v34, v171, v34, v32
	v_sub_f32_e32 v32, v171, v34
	v_exp_f32_e32 v32, v32
	v_mov_b32_e32 v171, v34
	v_pk_mul_f32 v[94:95], v[94:95], v[32:33] op_sel_hi:[1,0]
	v_pk_mul_f32 v[92:93], v[92:93], v[32:33] op_sel_hi:[1,0]
	v_pk_mul_f32 v[90:91], v[90:91], v[32:33] op_sel_hi:[1,0]
	v_pk_mul_f32 v[88:89], v[88:89], v[32:33] op_sel_hi:[1,0]
	v_pk_mul_f32 v[86:87], v[86:87], v[32:33] op_sel_hi:[1,0]
	v_pk_mul_f32 v[84:85], v[84:85], v[32:33] op_sel_hi:[1,0]
	v_pk_mul_f32 v[82:83], v[82:83], v[32:33] op_sel_hi:[1,0]
	v_pk_mul_f32 v[80:81], v[80:81], v[32:33] op_sel_hi:[1,0]
	v_pk_mul_f32 v[98:99], v[98:99], v[32:33] op_sel_hi:[1,0]
	v_pk_mul_f32 v[96:97], v[96:97], v[32:33] op_sel_hi:[1,0]
.LBB0_369:
	v_pk_add_f32 v[154:155], v[154:155], v[170:171] op_sel:[0,1] op_sel_hi:[1,1] neg_lo:[0,1] neg_hi:[0,1]
	v_pk_add_f32 v[152:153], v[152:153], v[170:171] op_sel:[0,1] op_sel_hi:[1,1] neg_lo:[0,1] neg_hi:[0,1]
	v_pk_add_f32 v[156:157], v[156:157], v[170:171] op_sel:[0,1] op_sel_hi:[1,1] neg_lo:[0,1] neg_hi:[0,1]
	v_pk_add_f32 v[158:159], v[158:159], v[170:171] op_sel:[0,1] op_sel_hi:[1,1] neg_lo:[0,1] neg_hi:[0,1]
	v_exp_f32_e32 v154, v154
	v_exp_f32_e32 v155, v155
	v_exp_f32_e32 v152, v152
	v_exp_f32_e32 v153, v153
	v_exp_f32_e32 v156, v156
	v_exp_f32_e32 v157, v157
	v_exp_f32_e32 v158, v158
	v_exp_f32_e32 v159, v159
	v_cvt_pk_bf16_f32 v155, v154, v155
	v_cvt_pk_bf16_f32 v154, v152, v153
	v_cvt_pk_bf16_f32 v152, v156, v157
	v_cvt_pk_bf16_f32 v153, v158, v159
	s_nop 1
	v_mfma_f32_16x16x32_bf16 v[92:95], v[0:3], v[152:155], v[92:95]
	v_mfma_f32_16x16x32_bf16 v[88:91], v[4:7], v[152:155], v[88:91]
	v_mfma_f32_16x16x32_bf16 v[84:87], v[8:11], v[152:155], v[84:87]
	v_mfma_f32_16x16x32_bf16 v[80:83], v[12:15], v[152:155], v[80:83]
	v_mfma_f32_16x16x32_bf16 v[96:99], v[36:39], v[152:155], v[96:99]
	ds_read_b128 v[152:155], v168 offset:26624
	s_waitcnt lgkmcnt(0)
	v_mfma_f32_16x16x32_bf16 v[24:27], v[24:27], v[152:155], 0
	v_mfma_f32_16x16x32_bf16 v[28:31], v[28:31], v[152:155], 0
	ds_read_b128 v[152:155], v168 offset:27648
	s_waitcnt lgkmcnt(0)
	v_mfma_f32_16x16x32_bf16 v[16:19], v[16:19], v[152:155], v[24:27]
	v_mfma_f32_16x16x32_bf16 v[20:23], v[20:23], v[152:155], v[28:31]
	s_nop 6
	v_max3_f32 v24, v16, v17, v18
	v_max3_f32 v26, v19, v20, v21
	v_max3_f32 v24, v24, v22, v23
	v_max_f32_e32 v24, v24, v26
	v_add_f32_e32 v25, 0x41000000, v169
	v_cmp_gt_f32_e32 vcc, v24, v25
	s_cbranch_vccz .LBB0_371
	v_mov_b32_e32 v25, v24
	s_nop 1
	v_permlane16_swap_b32 v24, v25
	s_nop 0
	v_max_f32_e32 v25, v25, v25
	v_max_f32_e32 v24, v24, v24
	v_max_f32_e32 v24, v24, v25
	v_mov_b32_e32 v25, v24
	s_nop 1
	v_permlane32_swap_b32 v24, v25
	s_nop 0
	v_max3_f32 v25, v169, v24, v25
	v_sub_f32_e32 v24, v169, v25
	v_exp_f32_e32 v24, v24
	v_mov_b32_e32 v169, v25
	v_pk_mul_f32 v[54:55], v[54:55], v[24:25] op_sel_hi:[1,0]
	v_pk_mul_f32 v[52:53], v[52:53], v[24:25] op_sel_hi:[1,0]
	v_pk_mul_f32 v[50:51], v[50:51], v[24:25] op_sel_hi:[1,0]
	v_pk_mul_f32 v[48:49], v[48:49], v[24:25] op_sel_hi:[1,0]
	v_pk_mul_f32 v[46:47], v[46:47], v[24:25] op_sel_hi:[1,0]
	v_pk_mul_f32 v[44:45], v[44:45], v[24:25] op_sel_hi:[1,0]
	v_pk_mul_f32 v[42:43], v[42:43], v[24:25] op_sel_hi:[1,0]
	v_pk_mul_f32 v[40:41], v[40:41], v[24:25] op_sel_hi:[1,0]
	v_pk_mul_f32 v[58:59], v[58:59], v[24:25] op_sel_hi:[1,0]
	v_pk_mul_f32 v[56:57], v[56:57], v[24:25] op_sel_hi:[1,0]
.LBB0_371:
	v_pk_add_f32 v[16:17], v[16:17], v[168:169] op_sel:[0,1] op_sel_hi:[1,1] neg_lo:[0,1] neg_hi:[0,1]
	v_pk_add_f32 v[18:19], v[18:19], v[168:169] op_sel:[0,1] op_sel_hi:[1,1] neg_lo:[0,1] neg_hi:[0,1]
	v_pk_add_f32 v[20:21], v[20:21], v[168:169] op_sel:[0,1] op_sel_hi:[1,1] neg_lo:[0,1] neg_hi:[0,1]
	v_pk_add_f32 v[22:23], v[22:23], v[168:169] op_sel:[0,1] op_sel_hi:[1,1] neg_lo:[0,1] neg_hi:[0,1]
	v_exp_f32_e32 v16, v16
	v_exp_f32_e32 v17, v17
	v_exp_f32_e32 v18, v18
	v_exp_f32_e32 v19, v19
	v_exp_f32_e32 v20, v20
	v_exp_f32_e32 v21, v21
	v_exp_f32_e32 v22, v22
	v_exp_f32_e32 v23, v23
	v_cvt_pk_bf16_f32 v16, v16, v17
	v_cvt_pk_bf16_f32 v17, v18, v19
	v_cvt_pk_bf16_f32 v18, v20, v21
	v_cvt_pk_bf16_f32 v19, v22, v23
	s_add_i32 s31, s30, -2
	s_nop 0
	v_mfma_f32_16x16x32_bf16 v[52:55], v[0:3], v[16:19], v[52:55]
	v_mfma_f32_16x16x32_bf16 v[48:51], v[4:7], v[16:19], v[48:51]
	v_mfma_f32_16x16x32_bf16 v[44:47], v[8:11], v[16:19], v[44:47]
	v_mfma_f32_16x16x32_bf16 v[40:43], v[12:15], v[16:19], v[40:43]
	v_mfma_f32_16x16x32_bf16 v[56:59], v[36:39], v[16:19], v[56:59]
	s_cmp_lt_u32 s31, 6
	s_cselect_b32 s0, s30, 0
	s_add_i32 s34, s0, s60
	ds_read_b128 v[8:11], v168 offset:20480
	s_lshl_b32 s0, s34, 1
	s_lshl_b64 s[40:41], s[0:1], 14
	v_lshl_add_u64 v[4:5], v[164:165], 0, s[40:41]
	global_load_dwordx4 v[24:27], v[4:5], off
	global_load_dwordx4 v[16:19], v[4:5], off offset:1024
	ds_read_b128 v[156:159], v168 offset:21504
	s_waitcnt vmcnt(9) lgkmcnt(1)
	v_mfma_f32_16x16x32_bf16 v[0:3], v[144:147], v[8:11], 0
	s_mov_b32 s35, s1
	v_add_co_u32_e32 v4, vcc, s72, v4
	s_lshl_b64 s[34:35], s[34:35], 15
	s_nop 0
	v_addc_co_u32_e32 v5, vcc, 0, v5, vcc
	v_lshl_add_u64 v[12:13], v[166:167], 0, s[34:35]
	s_waitcnt vmcnt(8) lgkmcnt(0)
	v_mfma_f32_16x16x32_bf16 v[152:155], v[140:143], v[156:159], v[0:3]
	global_load_dwordx4 v[28:31], v[4:5], off
	global_load_dwordx4 v[20:23], v[4:5], off offset:1024
	s_nop 0
	global_load_dwordx4 v[0:3], v[12:13], off
	global_load_dwordx4 v[4:7], v[12:13], off offset:1024
	s_nop 2
	s_waitcnt vmcnt(11)
	v_mfma_f32_16x16x32_bf16 v[174:177], v[148:151], v[8:11], 0
	global_load_dwordx4 v[8:11], v[12:13], off offset:2048
	s_nop 0
	global_load_dwordx4 v[12:15], v[12:13], off offset:3072
	s_waitcnt vmcnt(12)
	v_mfma_f32_16x16x32_bf16 v[156:159], v[136:139], v[156:159], v[174:177]
	s_nop 4
	v_max3_f32 v32, v152, v153, v154
	s_nop 1
	v_max3_f32 v35, v155, v156, v157
	v_max3_f32 v32, v32, v158, v159
	v_max_f32_e32 v32, v32, v35
	v_add_f32_e32 v34, 0x41000000, v170
	v_cmp_gt_f32_e32 vcc, v32, v34
	s_cbranch_vccz .LBB0_373
	v_mov_b32_e32 v34, v32
	s_nop 1
	v_permlane16_swap_b32 v32, v34
	s_nop 0
	v_max_f32_e32 v34, v34, v34
	v_max_f32_e32 v32, v32, v32
	v_max_f32_e32 v32, v32, v34
	v_mov_b32_e32 v34, v32
	s_nop 1
	v_permlane32_swap_b32 v34, v32
	s_nop 0
	v_max3_f32 v34, v170, v34, v32
	v_sub_f32_e32 v32, v170, v34
	v_exp_f32_e32 v32, v32
	v_mov_b32_e32 v170, v34
	v_pk_mul_f32 v[74:75], v[74:75], v[32:33] op_sel_hi:[1,0]
	v_pk_mul_f32 v[72:73], v[72:73], v[32:33] op_sel_hi:[1,0]
	v_pk_mul_f32 v[70:71], v[70:71], v[32:33] op_sel_hi:[1,0]
	v_pk_mul_f32 v[68:69], v[68:69], v[32:33] op_sel_hi:[1,0]
	v_pk_mul_f32 v[66:67], v[66:67], v[32:33] op_sel_hi:[1,0]
	v_pk_mul_f32 v[64:65], v[64:65], v[32:33] op_sel_hi:[1,0]
	v_pk_mul_f32 v[62:63], v[62:63], v[32:33] op_sel_hi:[1,0]
	v_pk_mul_f32 v[60:61], v[60:61], v[32:33] op_sel_hi:[1,0]
	v_pk_mul_f32 v[78:79], v[78:79], v[32:33] op_sel_hi:[1,0]
	v_pk_mul_f32 v[76:77], v[76:77], v[32:33] op_sel_hi:[1,0]
.LBB0_373:
	v_pk_add_f32 v[152:153], v[152:153], v[170:171] op_sel_hi:[1,0] neg_lo:[0,1] neg_hi:[0,1]
	v_pk_add_f32 v[154:155], v[154:155], v[170:171] op_sel_hi:[1,0] neg_lo:[0,1] neg_hi:[0,1]
	v_pk_add_f32 v[156:157], v[156:157], v[170:171] op_sel_hi:[1,0] neg_lo:[0,1] neg_hi:[0,1]
	v_pk_add_f32 v[158:159], v[158:159], v[170:171] op_sel_hi:[1,0] neg_lo:[0,1] neg_hi:[0,1]
	v_exp_f32_e32 v152, v152
	v_exp_f32_e32 v153, v153
	v_exp_f32_e32 v154, v154
	v_exp_f32_e32 v155, v155
	v_exp_f32_e32 v156, v156
	v_exp_f32_e32 v157, v157
	v_exp_f32_e32 v158, v158
	v_exp_f32_e32 v159, v159
	v_cvt_pk_bf16_f32 v152, v152, v153
	v_cvt_pk_bf16_f32 v153, v154, v155
	v_cvt_pk_bf16_f32 v154, v156, v157
	v_cvt_pk_bf16_f32 v155, v158, v159
	s_waitcnt vmcnt(11)
	s_nop 0
	v_mfma_f32_16x16x32_bf16 v[72:75], v[120:123], v[152:155], v[72:75]
	s_waitcnt vmcnt(10)
	v_mfma_f32_16x16x32_bf16 v[68:71], v[124:127], v[152:155], v[68:71]
	s_waitcnt vmcnt(9)
	v_mfma_f32_16x16x32_bf16 v[64:67], v[128:131], v[152:155], v[64:67]
	s_waitcnt vmcnt(8)
	v_mfma_f32_16x16x32_bf16 v[60:63], v[132:135], v[152:155], v[60:63]
	v_mfma_f32_16x16x32_bf16 v[76:79], v[36:39], v[152:155], v[76:79]
	ds_read_b128 v[152:155], v168 offset:22528
	ds_read_b128 v[174:177], v168 offset:23552
	s_waitcnt lgkmcnt(1)
	v_mfma_f32_16x16x32_bf16 v[156:159], v[144:147], v[152:155], 0
	v_mfma_f32_16x16x32_bf16 v[152:155], v[148:151], v[152:155], 0
	s_waitcnt lgkmcnt(0)
	v_mfma_f32_16x16x32_bf16 v[156:159], v[140:143], v[174:177], v[156:159]
	v_mfma_f32_16x16x32_bf16 v[152:155], v[136:139], v[174:177], v[152:155]
	s_nop 6
	v_max3_f32 v32, v156, v157, v158
	v_max3_f32 v35, v159, v152, v153
	v_max3_f32 v32, v32, v154, v155
	v_max_f32_e32 v32, v32, v35
	v_add_f32_e32 v34, 0x41000000, v172
	v_cmp_gt_f32_e32 vcc, v32, v34
	s_cbranch_vccz .LBB0_375
	v_mov_b32_e32 v34, v32
	s_nop 1
	v_permlane16_swap_b32 v32, v34
	s_nop 0
	v_max_f32_e32 v34, v34, v34
	v_max_f32_e32 v32, v32, v32
	v_max_f32_e32 v32, v32, v34
	v_mov_b32_e32 v34, v32
	s_nop 1
	v_permlane32_swap_b32 v32, v34
	s_nop 0
	v_max3_f32 v34, v172, v32, v34
	v_sub_f32_e32 v32, v172, v34
	v_exp_f32_e32 v32, v32
	v_mov_b32_e32 v172, v34
	v_pk_mul_f32 v[114:115], v[114:115], v[32:33] op_sel_hi:[1,0]
	v_pk_mul_f32 v[112:113], v[112:113], v[32:33] op_sel_hi:[1,0]
	v_pk_mul_f32 v[110:111], v[110:111], v[32:33] op_sel_hi:[1,0]
	v_pk_mul_f32 v[108:109], v[108:109], v[32:33] op_sel_hi:[1,0]
	v_pk_mul_f32 v[106:107], v[106:107], v[32:33] op_sel_hi:[1,0]
	v_pk_mul_f32 v[104:105], v[104:105], v[32:33] op_sel_hi:[1,0]
	v_pk_mul_f32 v[102:103], v[102:103], v[32:33] op_sel_hi:[1,0]
	v_pk_mul_f32 v[100:101], v[100:101], v[32:33] op_sel_hi:[1,0]
	v_pk_mul_f32 v[118:119], v[118:119], v[32:33] op_sel_hi:[1,0]
	v_pk_mul_f32 v[116:117], v[116:117], v[32:33] op_sel_hi:[1,0]
.LBB0_375:
	v_pk_add_f32 v[154:155], v[154:155], v[172:173] op_sel_hi:[1,0] neg_lo:[0,1] neg_hi:[0,1]
	v_pk_add_f32 v[152:153], v[152:153], v[172:173] op_sel_hi:[1,0] neg_lo:[0,1] neg_hi:[0,1]
	v_pk_add_f32 v[156:157], v[156:157], v[172:173] op_sel_hi:[1,0] neg_lo:[0,1] neg_hi:[0,1]
	v_pk_add_f32 v[158:159], v[158:159], v[172:173] op_sel_hi:[1,0] neg_lo:[0,1] neg_hi:[0,1]
	v_exp_f32_e32 v154, v154
	v_exp_f32_e32 v155, v155
	v_exp_f32_e32 v152, v152
	v_exp_f32_e32 v153, v153
	v_exp_f32_e32 v156, v156
	v_exp_f32_e32 v157, v157
	v_exp_f32_e32 v158, v158
	v_exp_f32_e32 v159, v159
	v_cvt_pk_bf16_f32 v155, v154, v155
	v_cvt_pk_bf16_f32 v154, v152, v153
	v_cvt_pk_bf16_f32 v152, v156, v157
	v_cvt_pk_bf16_f32 v153, v158, v159
	s_nop 1
	v_mfma_f32_16x16x32_bf16 v[112:115], v[120:123], v[152:155], v[112:115]
	v_mfma_f32_16x16x32_bf16 v[108:111], v[124:127], v[152:155], v[108:111]
	v_mfma_f32_16x16x32_bf16 v[104:107], v[128:131], v[152:155], v[104:107]
	v_mfma_f32_16x16x32_bf16 v[100:103], v[132:135], v[152:155], v[100:103]
	v_mfma_f32_16x16x32_bf16 v[116:119], v[36:39], v[152:155], v[116:119]
	ds_read_b128 v[152:155], v168 offset:24576
	ds_read_b128 v[174:177], v168 offset:25600
	s_waitcnt lgkmcnt(1)
	v_mfma_f32_16x16x32_bf16 v[156:159], v[144:147], v[152:155], 0
	v_mfma_f32_16x16x32_bf16 v[152:155], v[148:151], v[152:155], 0
	s_waitcnt lgkmcnt(0)
	v_mfma_f32_16x16x32_bf16 v[156:159], v[140:143], v[174:177], v[156:159]
	v_mfma_f32_16x16x32_bf16 v[152:155], v[136:139], v[174:177], v[152:155]
	s_nop 6
	v_max3_f32 v32, v156, v157, v158
	v_max3_f32 v35, v159, v152, v153
	v_max3_f32 v32, v32, v154, v155
	v_max_f32_e32 v32, v32, v35
	v_add_f32_e32 v34, 0x41000000, v171
	v_cmp_gt_f32_e32 vcc, v32, v34
	s_cbranch_vccz .LBB0_377
	v_mov_b32_e32 v34, v32
	s_nop 1
	v_permlane16_swap_b32 v32, v34
	s_nop 0
	v_max_f32_e32 v34, v34, v34
	v_max_f32_e32 v32, v32, v32
	v_max_f32_e32 v32, v32, v34
	v_mov_b32_e32 v34, v32
	s_nop 1
	v_permlane32_swap_b32 v32, v34
	s_nop 0
	v_max3_f32 v34, v171, v32, v34
	v_sub_f32_e32 v32, v171, v34
	v_exp_f32_e32 v32, v32
	v_mov_b32_e32 v171, v34
	v_pk_mul_f32 v[94:95], v[94:95], v[32:33] op_sel_hi:[1,0]
	v_pk_mul_f32 v[92:93], v[92:93], v[32:33] op_sel_hi:[1,0]
	v_pk_mul_f32 v[90:91], v[90:91], v[32:33] op_sel_hi:[1,0]
	v_pk_mul_f32 v[88:89], v[88:89], v[32:33] op_sel_hi:[1,0]
	v_pk_mul_f32 v[86:87], v[86:87], v[32:33] op_sel_hi:[1,0]
	v_pk_mul_f32 v[84:85], v[84:85], v[32:33] op_sel_hi:[1,0]
	v_pk_mul_f32 v[82:83], v[82:83], v[32:33] op_sel_hi:[1,0]
	v_pk_mul_f32 v[80:81], v[80:81], v[32:33] op_sel_hi:[1,0]
	v_pk_mul_f32 v[98:99], v[98:99], v[32:33] op_sel_hi:[1,0]
	v_pk_mul_f32 v[96:97], v[96:97], v[32:33] op_sel_hi:[1,0]
.LBB0_377:
	v_pk_add_f32 v[154:155], v[154:155], v[170:171] op_sel:[0,1] op_sel_hi:[1,1] neg_lo:[0,1] neg_hi:[0,1]
	v_pk_add_f32 v[152:153], v[152:153], v[170:171] op_sel:[0,1] op_sel_hi:[1,1] neg_lo:[0,1] neg_hi:[0,1]
	v_pk_add_f32 v[156:157], v[156:157], v[170:171] op_sel:[0,1] op_sel_hi:[1,1] neg_lo:[0,1] neg_hi:[0,1]
	v_pk_add_f32 v[158:159], v[158:159], v[170:171] op_sel:[0,1] op_sel_hi:[1,1] neg_lo:[0,1] neg_hi:[0,1]
	v_exp_f32_e32 v154, v154
	v_exp_f32_e32 v155, v155
	v_exp_f32_e32 v152, v152
	v_exp_f32_e32 v153, v153
	v_exp_f32_e32 v156, v156
	v_exp_f32_e32 v157, v157
	v_exp_f32_e32 v158, v158
	v_exp_f32_e32 v159, v159
	v_cvt_pk_bf16_f32 v155, v154, v155
	v_cvt_pk_bf16_f32 v154, v152, v153
	v_cvt_pk_bf16_f32 v152, v156, v157
	v_cvt_pk_bf16_f32 v153, v158, v159
	s_nop 1
	v_mfma_f32_16x16x32_bf16 v[92:95], v[120:123], v[152:155], v[92:95]
	v_mfma_f32_16x16x32_bf16 v[88:91], v[124:127], v[152:155], v[88:91]
	v_mfma_f32_16x16x32_bf16 v[84:87], v[128:131], v[152:155], v[84:87]
	v_mfma_f32_16x16x32_bf16 v[80:83], v[132:135], v[152:155], v[80:83]
	v_mfma_f32_16x16x32_bf16 v[96:99], v[36:39], v[152:155], v[96:99]
	ds_read_b128 v[152:155], v168 offset:26624
	s_waitcnt lgkmcnt(0)
	v_mfma_f32_16x16x32_bf16 v[144:147], v[144:147], v[152:155], 0
	v_mfma_f32_16x16x32_bf16 v[148:151], v[148:151], v[152:155], 0
	ds_read_b128 v[152:155], v168 offset:27648
	s_waitcnt lgkmcnt(0)
	v_mfma_f32_16x16x32_bf16 v[140:143], v[140:143], v[152:155], v[144:147]
	v_mfma_f32_16x16x32_bf16 v[136:139], v[136:139], v[152:155], v[148:151]
	s_nop 6
	v_max3_f32 v32, v140, v141, v142
	v_max3_f32 v35, v143, v136, v137
	v_max3_f32 v32, v32, v138, v139
	v_max_f32_e32 v32, v32, v35
	v_add_f32_e32 v34, 0x41000000, v169
	v_cmp_gt_f32_e32 vcc, v32, v34
	s_cbranch_vccz .LBB0_362
	v_mov_b32_e32 v34, v32
	s_nop 1
	v_permlane16_swap_b32 v32, v34
	s_nop 0
	v_max_f32_e32 v34, v34, v34
	v_max_f32_e32 v32, v32, v32
	v_max_f32_e32 v32, v32, v34
	v_mov_b32_e32 v34, v32
	s_nop 1
	v_permlane32_swap_b32 v32, v34
	s_nop 0
	v_max3_f32 v34, v169, v32, v34
	v_sub_f32_e32 v32, v169, v34
	v_exp_f32_e32 v32, v32
	v_mov_b32_e32 v169, v34
	v_pk_mul_f32 v[54:55], v[54:55], v[32:33] op_sel_hi:[1,0]
	v_pk_mul_f32 v[52:53], v[52:53], v[32:33] op_sel_hi:[1,0]
	v_pk_mul_f32 v[50:51], v[50:51], v[32:33] op_sel_hi:[1,0]
	v_pk_mul_f32 v[48:49], v[48:49], v[32:33] op_sel_hi:[1,0]
	v_pk_mul_f32 v[46:47], v[46:47], v[32:33] op_sel_hi:[1,0]
	v_pk_mul_f32 v[44:45], v[44:45], v[32:33] op_sel_hi:[1,0]
	v_pk_mul_f32 v[42:43], v[42:43], v[32:33] op_sel_hi:[1,0]
	v_pk_mul_f32 v[40:41], v[40:41], v[32:33] op_sel_hi:[1,0]
	v_pk_mul_f32 v[58:59], v[58:59], v[32:33] op_sel_hi:[1,0]
	v_pk_mul_f32 v[56:57], v[56:57], v[32:33] op_sel_hi:[1,0]
	s_branch .LBB0_362

.LBB0_381:
	v_pk_add_f32 v[58:59], v[58:59], v[168:169] op_sel_hi:[1,0] neg_lo:[0,1] neg_hi:[0,1]
	v_pk_add_f32 v[56:57], v[56:57], v[168:169] op_sel_hi:[1,0] neg_lo:[0,1] neg_hi:[0,1]
	v_pk_add_f32 v[60:61], v[60:61], v[168:169] op_sel_hi:[1,0] neg_lo:[0,1] neg_hi:[0,1]
	v_pk_add_f32 v[62:63], v[62:63], v[168:169] op_sel_hi:[1,0] neg_lo:[0,1] neg_hi:[0,1]
	v_exp_f32_e32 v58, v58
	v_exp_f32_e32 v59, v59
	v_exp_f32_e32 v56, v56
	v_exp_f32_e32 v57, v57
	v_exp_f32_e32 v60, v60
	v_exp_f32_e32 v61, v61
	v_exp_f32_e32 v62, v62
	v_exp_f32_e32 v63, v63
	v_mov_b32_e32 v37, v36
	v_mov_b32_e32 v38, v36
	v_mov_b32_e32 v39, v36
	v_cvt_pk_bf16_f32 v59, v58, v59
	v_cvt_pk_bf16_f32 v58, v56, v57
	v_cvt_pk_bf16_f32 v56, v60, v61
	v_cvt_pk_bf16_f32 v57, v62, v63
	s_nop 1
	v_mfma_f32_16x16x32_bf16 v[84:87], v[40:43], v[56:59], v[84:87]
	v_mfma_f32_16x16x32_bf16 v[80:83], v[44:47], v[56:59], v[80:83]
	v_mfma_f32_16x16x32_bf16 v[76:79], v[48:51], v[56:59], v[76:79]
	v_mfma_f32_16x16x32_bf16 v[72:75], v[52:55], v[56:59], v[72:75]
	v_mfma_f32_16x16x32_bf16 v[88:91], v[36:39], v[56:59], v[88:91]
	s_add_i32 s25, s25, 2
	s_add_u32 s26, s26, 0x10000
	s_addc_u32 s27, s27, 0
	s_add_u32 s34, s34, 0x10000
	s_addc_u32 s35, s35, 0
	s_cmp_lt_u32 s30, 6
	s_cbranch_scc0 .LBB0_398

.LBB0_384:
	v_pk_add_f32 v[152:153], v[152:153], v[170:171] op_sel:[0,1] op_sel_hi:[1,1] neg_lo:[0,1] neg_hi:[0,1]
	v_pk_add_f32 v[154:155], v[154:155], v[170:171] op_sel:[0,1] op_sel_hi:[1,1] neg_lo:[0,1] neg_hi:[0,1]
	v_pk_add_f32 v[156:157], v[156:157], v[170:171] op_sel:[0,1] op_sel_hi:[1,1] neg_lo:[0,1] neg_hi:[0,1]
	v_pk_add_f32 v[158:159], v[158:159], v[170:171] op_sel:[0,1] op_sel_hi:[1,1] neg_lo:[0,1] neg_hi:[0,1]
	v_exp_f32_e32 v152, v152
	v_exp_f32_e32 v153, v153
	v_exp_f32_e32 v154, v154
	v_exp_f32_e32 v155, v155
	v_exp_f32_e32 v156, v156
	v_exp_f32_e32 v157, v157
	v_exp_f32_e32 v158, v158
	v_exp_f32_e32 v159, v159
	v_mov_b32_e32 v37, v36
	v_mov_b32_e32 v38, v36
	v_mov_b32_e32 v39, v36
	v_cvt_pk_bf16_f32 v152, v152, v153
	v_cvt_pk_bf16_f32 v153, v154, v155
	v_cvt_pk_bf16_f32 v154, v156, v157
	v_cvt_pk_bf16_f32 v155, v158, v159
	s_waitcnt vmcnt(11)
	s_nop 0
	v_mfma_f32_16x16x32_bf16 v[144:147], v[0:3], v[152:155], v[144:147]
	s_waitcnt vmcnt(10)
	v_mfma_f32_16x16x32_bf16 v[140:143], v[4:7], v[152:155], v[140:143]
	s_waitcnt vmcnt(9)
	v_mfma_f32_16x16x32_bf16 v[136:139], v[8:11], v[152:155], v[136:139]
	s_waitcnt vmcnt(8)
	v_mfma_f32_16x16x32_bf16 v[132:135], v[12:15], v[152:155], v[132:135]
	v_mfma_f32_16x16x32_bf16 v[148:151], v[36:39], v[152:155], v[148:151]
	ds_read_b128 v[152:155], v167 offset:22528
	ds_read_b128 v[172:175], v167 offset:23552
	s_waitcnt lgkmcnt(1)
	v_mfma_f32_16x16x32_bf16 v[156:159], v[20:23], v[152:155], 0
	v_mfma_f32_16x16x32_bf16 v[152:155], v[28:31], v[152:155], 0
	s_waitcnt lgkmcnt(0)
	v_mfma_f32_16x16x32_bf16 v[156:159], v[16:19], v[172:175], v[156:159]
	v_mfma_f32_16x16x32_bf16 v[152:155], v[24:27], v[172:175], v[152:155]
	s_nop 6
	v_max3_f32 v32, v156, v157, v158
	v_max3_f32 v35, v159, v152, v153
	v_max3_f32 v32, v32, v154, v155
	v_max_f32_e32 v32, v32, v35
	v_add_f32_e32 v34, 0x41000000, v170
	v_cmp_gt_f32_e32 vcc, v32, v34
	s_cbranch_vccz .LBB0_386
	v_mov_b32_e32 v34, v32
	s_nop 1
	v_permlane16_swap_b32 v32, v34
	s_nop 0
	v_max_f32_e32 v34, v34, v34
	v_max_f32_e32 v32, v32, v32
	v_max_f32_e32 v32, v32, v34
	v_mov_b32_e32 v34, v32
	s_nop 1
	v_permlane32_swap_b32 v32, v34
	s_nop 0
	v_max3_f32 v34, v170, v32, v34
	v_sub_f32_e32 v32, v170, v34
	v_exp_f32_e32 v32, v32
	v_mov_b32_e32 v170, v34
	v_pk_mul_f32 v[126:127], v[126:127], v[32:33] op_sel_hi:[1,0]
	v_pk_mul_f32 v[124:125], v[124:125], v[32:33] op_sel_hi:[1,0]
	v_pk_mul_f32 v[122:123], v[122:123], v[32:33] op_sel_hi:[1,0]
	v_pk_mul_f32 v[120:121], v[120:121], v[32:33] op_sel_hi:[1,0]
	v_pk_mul_f32 v[118:119], v[118:119], v[32:33] op_sel_hi:[1,0]
	v_pk_mul_f32 v[116:117], v[116:117], v[32:33] op_sel_hi:[1,0]
	v_pk_mul_f32 v[114:115], v[114:115], v[32:33] op_sel_hi:[1,0]
	v_pk_mul_f32 v[112:113], v[112:113], v[32:33] op_sel_hi:[1,0]
	v_pk_mul_f32 v[130:131], v[130:131], v[32:33] op_sel_hi:[1,0]
	v_pk_mul_f32 v[128:129], v[128:129], v[32:33] op_sel_hi:[1,0]
.LBB0_386:
	v_pk_add_f32 v[154:155], v[154:155], v[170:171] op_sel_hi:[1,0] neg_lo:[0,1] neg_hi:[0,1]
	v_pk_add_f32 v[152:153], v[152:153], v[170:171] op_sel_hi:[1,0] neg_lo:[0,1] neg_hi:[0,1]
	v_pk_add_f32 v[156:157], v[156:157], v[170:171] op_sel_hi:[1,0] neg_lo:[0,1] neg_hi:[0,1]
	v_pk_add_f32 v[158:159], v[158:159], v[170:171] op_sel_hi:[1,0] neg_lo:[0,1] neg_hi:[0,1]
	v_exp_f32_e32 v154, v154
	v_exp_f32_e32 v155, v155
	v_exp_f32_e32 v152, v152
	v_exp_f32_e32 v153, v153
	v_exp_f32_e32 v156, v156
	v_exp_f32_e32 v157, v157
	v_exp_f32_e32 v158, v158
	v_exp_f32_e32 v159, v159
	v_cvt_pk_bf16_f32 v155, v154, v155
	v_cvt_pk_bf16_f32 v154, v152, v153
	v_cvt_pk_bf16_f32 v152, v156, v157
	v_cvt_pk_bf16_f32 v153, v158, v159
	s_nop 1
	v_mfma_f32_16x16x32_bf16 v[124:127], v[0:3], v[152:155], v[124:127]
	v_mfma_f32_16x16x32_bf16 v[120:123], v[4:7], v[152:155], v[120:123]
	v_mfma_f32_16x16x32_bf16 v[116:119], v[8:11], v[152:155], v[116:119]
	v_mfma_f32_16x16x32_bf16 v[112:115], v[12:15], v[152:155], v[112:115]
	v_mfma_f32_16x16x32_bf16 v[128:131], v[36:39], v[152:155], v[128:131]
	ds_read_b128 v[152:155], v167 offset:24576
	ds_read_b128 v[172:175], v167 offset:25600
	s_waitcnt lgkmcnt(1)
	v_mfma_f32_16x16x32_bf16 v[156:159], v[20:23], v[152:155], 0
	v_mfma_f32_16x16x32_bf16 v[152:155], v[28:31], v[152:155], 0
	s_waitcnt lgkmcnt(0)
	v_mfma_f32_16x16x32_bf16 v[156:159], v[16:19], v[172:175], v[156:159]
	v_mfma_f32_16x16x32_bf16 v[152:155], v[24:27], v[172:175], v[152:155]
	s_nop 6
	v_max3_f32 v32, v156, v157, v158
	v_max3_f32 v35, v159, v152, v153
	v_max3_f32 v32, v32, v154, v155
	v_max_f32_e32 v32, v32, v35
	v_add_f32_e32 v34, 0x41000000, v169
	v_cmp_gt_f32_e32 vcc, v32, v34
	s_cbranch_vccz .LBB0_388
	v_mov_b32_e32 v34, v32
	s_nop 1
	v_permlane16_swap_b32 v32, v34
	s_nop 0
	v_max_f32_e32 v34, v34, v34
	v_max_f32_e32 v32, v32, v32
	v_max_f32_e32 v32, v32, v34
	v_mov_b32_e32 v34, v32
	s_nop 1
	v_permlane32_swap_b32 v32, v34
	s_nop 0
	v_max3_f32 v34, v169, v32, v34
	v_sub_f32_e32 v32, v169, v34
	v_exp_f32_e32 v32, v32
	v_mov_b32_e32 v169, v34
	v_pk_mul_f32 v[106:107], v[106:107], v[32:33] op_sel_hi:[1,0]
	v_pk_mul_f32 v[104:105], v[104:105], v[32:33] op_sel_hi:[1,0]
	v_pk_mul_f32 v[102:103], v[102:103], v[32:33] op_sel_hi:[1,0]
	v_pk_mul_f32 v[100:101], v[100:101], v[32:33] op_sel_hi:[1,0]
	v_pk_mul_f32 v[98:99], v[98:99], v[32:33] op_sel_hi:[1,0]
	v_pk_mul_f32 v[96:97], v[96:97], v[32:33] op_sel_hi:[1,0]
	v_pk_mul_f32 v[94:95], v[94:95], v[32:33] op_sel_hi:[1,0]
	v_pk_mul_f32 v[92:93], v[92:93], v[32:33] op_sel_hi:[1,0]
	v_pk_mul_f32 v[110:111], v[110:111], v[32:33] op_sel_hi:[1,0]
	v_pk_mul_f32 v[108:109], v[108:109], v[32:33] op_sel_hi:[1,0]
.LBB0_388:
	v_pk_add_f32 v[154:155], v[154:155], v[168:169] op_sel:[0,1] op_sel_hi:[1,1] neg_lo:[0,1] neg_hi:[0,1]
	v_pk_add_f32 v[152:153], v[152:153], v[168:169] op_sel:[0,1] op_sel_hi:[1,1] neg_lo:[0,1] neg_hi:[0,1]
	v_pk_add_f32 v[156:157], v[156:157], v[168:169] op_sel:[0,1] op_sel_hi:[1,1] neg_lo:[0,1] neg_hi:[0,1]
	v_pk_add_f32 v[158:159], v[158:159], v[168:169] op_sel:[0,1] op_sel_hi:[1,1] neg_lo:[0,1] neg_hi:[0,1]
	v_exp_f32_e32 v154, v154
	v_exp_f32_e32 v155, v155
	v_exp_f32_e32 v152, v152
	v_exp_f32_e32 v153, v153
	v_exp_f32_e32 v156, v156
	v_exp_f32_e32 v157, v157
	v_exp_f32_e32 v158, v158
	v_exp_f32_e32 v159, v159
	v_cvt_pk_bf16_f32 v155, v154, v155
	v_cvt_pk_bf16_f32 v154, v152, v153
	v_cvt_pk_bf16_f32 v152, v156, v157
	v_cvt_pk_bf16_f32 v153, v158, v159
	s_nop 1
	v_mfma_f32_16x16x32_bf16 v[104:107], v[0:3], v[152:155], v[104:107]
	v_mfma_f32_16x16x32_bf16 v[100:103], v[4:7], v[152:155], v[100:103]
	v_mfma_f32_16x16x32_bf16 v[96:99], v[8:11], v[152:155], v[96:99]
	v_mfma_f32_16x16x32_bf16 v[92:95], v[12:15], v[152:155], v[92:95]
	v_mfma_f32_16x16x32_bf16 v[108:111], v[36:39], v[152:155], v[108:111]
	ds_read_b128 v[152:155], v167 offset:26624
	s_waitcnt lgkmcnt(0)
	v_mfma_f32_16x16x32_bf16 v[20:23], v[20:23], v[152:155], 0
	v_mfma_f32_16x16x32_bf16 v[28:31], v[28:31], v[152:155], 0
	ds_read_b128 v[152:155], v167 offset:27648
	s_waitcnt lgkmcnt(0)
	v_mfma_f32_16x16x32_bf16 v[16:19], v[16:19], v[152:155], v[20:23]
	s_nop 7
	v_mfma_f32_16x16x32_bf16 v[20:23], v[24:27], v[152:155], v[28:31]
	s_nop 7
	v_max3_f32 v24, v16, v17, v18
	v_max3_f32 v25, v19, v20, v21
	v_max3_f32 v24, v24, v22, v23
	v_max_f32_e32 v24, v24, v25
	v_add_f32_e32 v25, 0x41000000, v168
	v_cmp_gt_f32_e32 vcc, v24, v25
	s_cbranch_vccz .LBB0_390
	v_mov_b32_e32 v25, v24
	s_nop 1
	v_permlane16_swap_b32 v24, v25
	s_nop 0
	v_max_f32_e32 v25, v25, v25
	v_max_f32_e32 v24, v24, v24
	v_max_f32_e32 v24, v24, v25
	v_mov_b32_e32 v25, v24
	s_nop 1
	v_permlane32_swap_b32 v24, v25
	s_nop 0
	v_max3_f32 v25, v168, v24, v25
	v_sub_f32_e32 v24, v168, v25
	v_exp_f32_e32 v24, v24
	v_mov_b32_e32 v168, v25
	v_pk_mul_f32 v[86:87], v[86:87], v[24:25] op_sel_hi:[1,0]
	v_pk_mul_f32 v[84:85], v[84:85], v[24:25] op_sel_hi:[1,0]
	v_pk_mul_f32 v[82:83], v[82:83], v[24:25] op_sel_hi:[1,0]
	v_pk_mul_f32 v[80:81], v[80:81], v[24:25] op_sel_hi:[1,0]
	v_pk_mul_f32 v[78:79], v[78:79], v[24:25] op_sel_hi:[1,0]
	v_pk_mul_f32 v[76:77], v[76:77], v[24:25] op_sel_hi:[1,0]
	v_pk_mul_f32 v[74:75], v[74:75], v[24:25] op_sel_hi:[1,0]
	v_pk_mul_f32 v[72:73], v[72:73], v[24:25] op_sel_hi:[1,0]
	v_pk_mul_f32 v[90:91], v[90:91], v[24:25] op_sel_hi:[1,0]
	v_pk_mul_f32 v[88:89], v[88:89], v[24:25] op_sel_hi:[1,0]
.LBB0_390:
	v_pk_add_f32 v[16:17], v[16:17], v[168:169] op_sel_hi:[1,0] neg_lo:[0,1] neg_hi:[0,1]
	v_pk_add_f32 v[18:19], v[18:19], v[168:169] op_sel_hi:[1,0] neg_lo:[0,1] neg_hi:[0,1]
	v_pk_add_f32 v[20:21], v[20:21], v[168:169] op_sel_hi:[1,0] neg_lo:[0,1] neg_hi:[0,1]
	v_pk_add_f32 v[22:23], v[22:23], v[168:169] op_sel_hi:[1,0] neg_lo:[0,1] neg_hi:[0,1]
	v_exp_f32_e32 v16, v16
	v_exp_f32_e32 v17, v17
	v_exp_f32_e32 v18, v18
	v_exp_f32_e32 v19, v19
	v_exp_f32_e32 v20, v20
	v_exp_f32_e32 v21, v21
	v_exp_f32_e32 v22, v22
	v_exp_f32_e32 v23, v23
	v_cvt_pk_bf16_f32 v16, v16, v17
	v_cvt_pk_bf16_f32 v17, v18, v19
	v_cvt_pk_bf16_f32 v18, v20, v21
	v_cvt_pk_bf16_f32 v19, v22, v23
	s_add_i32 s30, s25, -2
	s_nop 0
	v_mfma_f32_16x16x32_bf16 v[84:87], v[0:3], v[16:19], v[84:87]
	v_mfma_f32_16x16x32_bf16 v[80:83], v[4:7], v[16:19], v[80:83]
	v_mfma_f32_16x16x32_bf16 v[76:79], v[8:11], v[16:19], v[76:79]
	v_mfma_f32_16x16x32_bf16 v[72:75], v[12:15], v[16:19], v[72:75]
	v_mfma_f32_16x16x32_bf16 v[88:91], v[36:39], v[16:19], v[88:91]
	s_cmp_lt_u32 s30, 6
	s_cselect_b32 s0, s25, 0
	s_add_i32 s40, s0, s60
	ds_read_b128 v[8:11], v167 offset:20480
	s_lshl_b32 s0, s40, 1
	s_lshl_b64 s[42:43], s[0:1], 14
	v_lshl_add_u64 v[4:5], v[162:163], 0, s[42:43]
	global_load_dwordx4 v[20:23], v[4:5], off
	global_load_dwordx4 v[16:19], v[4:5], off offset:1024
	ds_read_b128 v[156:159], v167 offset:21504
	s_waitcnt vmcnt(9) lgkmcnt(1)
	v_mfma_f32_16x16x32_bf16 v[0:3], v[64:67], v[8:11], 0
	s_mov_b32 s41, s1
	v_add_co_u32_e32 v4, vcc, s72, v4
	s_lshl_b64 s[40:41], s[40:41], 15
	s_nop 0
	v_addc_co_u32_e32 v5, vcc, 0, v5, vcc
	v_lshl_add_u64 v[12:13], v[164:165], 0, s[40:41]
	s_waitcnt vmcnt(8) lgkmcnt(0)
	v_mfma_f32_16x16x32_bf16 v[152:155], v[60:63], v[156:159], v[0:3]
	global_load_dwordx4 v[28:31], v[4:5], off
	global_load_dwordx4 v[24:27], v[4:5], off offset:1024
	s_nop 0
	global_load_dwordx4 v[0:3], v[12:13], off
	global_load_dwordx4 v[4:7], v[12:13], off offset:1024
	s_nop 2
	s_waitcnt vmcnt(11)
	v_mfma_f32_16x16x32_bf16 v[172:175], v[68:71], v[8:11], 0
	global_load_dwordx4 v[8:11], v[12:13], off offset:2048
	s_nop 0
	global_load_dwordx4 v[12:15], v[12:13], off offset:3072
	s_waitcnt vmcnt(12)
	v_mfma_f32_16x16x32_bf16 v[156:159], v[56:59], v[156:159], v[172:175]
	s_nop 4
	v_max3_f32 v32, v152, v153, v154
	s_nop 1
	v_max3_f32 v35, v155, v156, v157
	v_max3_f32 v32, v32, v158, v159
	v_max_f32_e32 v32, v32, v35
	v_add_f32_e32 v34, 0x41000000, v171
	v_cmp_gt_f32_e32 vcc, v32, v34
	s_cbranch_vccz .LBB0_392
	v_mov_b32_e32 v34, v32
	s_nop 1
	v_permlane16_swap_b32 v32, v34
	s_nop 0
	v_max_f32_e32 v34, v34, v34
	v_max_f32_e32 v32, v32, v32
	v_max_f32_e32 v32, v32, v34
	v_mov_b32_e32 v34, v32
	s_nop 1
	v_permlane32_swap_b32 v32, v34
	s_nop 0
	v_max3_f32 v34, v171, v32, v34
	v_sub_f32_e32 v32, v171, v34
	v_exp_f32_e32 v32, v32
	v_mov_b32_e32 v171, v34
	v_pk_mul_f32 v[146:147], v[146:147], v[32:33] op_sel_hi:[1,0]
	v_pk_mul_f32 v[144:145], v[144:145], v[32:33] op_sel_hi:[1,0]
	v_pk_mul_f32 v[142:143], v[142:143], v[32:33] op_sel_hi:[1,0]
	v_pk_mul_f32 v[140:141], v[140:141], v[32:33] op_sel_hi:[1,0]
	v_pk_mul_f32 v[138:139], v[138:139], v[32:33] op_sel_hi:[1,0]
	v_pk_mul_f32 v[136:137], v[136:137], v[32:33] op_sel_hi:[1,0]
	v_pk_mul_f32 v[134:135], v[134:135], v[32:33] op_sel_hi:[1,0]
	v_pk_mul_f32 v[132:133], v[132:133], v[32:33] op_sel_hi:[1,0]
	v_pk_mul_f32 v[150:151], v[150:151], v[32:33] op_sel_hi:[1,0]
	v_pk_mul_f32 v[148:149], v[148:149], v[32:33] op_sel_hi:[1,0]
.LBB0_392:
	v_pk_add_f32 v[152:153], v[152:153], v[170:171] op_sel:[0,1] op_sel_hi:[1,1] neg_lo:[0,1] neg_hi:[0,1]
	v_pk_add_f32 v[154:155], v[154:155], v[170:171] op_sel:[0,1] op_sel_hi:[1,1] neg_lo:[0,1] neg_hi:[0,1]
	v_pk_add_f32 v[156:157], v[156:157], v[170:171] op_sel:[0,1] op_sel_hi:[1,1] neg_lo:[0,1] neg_hi:[0,1]
	v_pk_add_f32 v[158:159], v[158:159], v[170:171] op_sel:[0,1] op_sel_hi:[1,1] neg_lo:[0,1] neg_hi:[0,1]
	v_exp_f32_e32 v152, v152
	v_exp_f32_e32 v153, v153
	v_exp_f32_e32 v154, v154
	v_exp_f32_e32 v155, v155
	v_exp_f32_e32 v156, v156
	v_exp_f32_e32 v157, v157
	v_exp_f32_e32 v158, v158
	v_exp_f32_e32 v159, v159
	v_cvt_pk_bf16_f32 v152, v152, v153
	v_cvt_pk_bf16_f32 v153, v154, v155
	v_cvt_pk_bf16_f32 v154, v156, v157
	v_cvt_pk_bf16_f32 v155, v158, v159
	s_waitcnt vmcnt(11)
	s_nop 0
	v_mfma_f32_16x16x32_bf16 v[144:147], v[40:43], v[152:155], v[144:147]
	s_waitcnt vmcnt(10)
	v_mfma_f32_16x16x32_bf16 v[140:143], v[44:47], v[152:155], v[140:143]
	s_waitcnt vmcnt(9)
	v_mfma_f32_16x16x32_bf16 v[136:139], v[48:51], v[152:155], v[136:139]
	s_waitcnt vmcnt(8)
	v_mfma_f32_16x16x32_bf16 v[132:135], v[52:55], v[152:155], v[132:135]
	v_mfma_f32_16x16x32_bf16 v[148:151], v[36:39], v[152:155], v[148:151]
	ds_read_b128 v[152:155], v167 offset:22528
	ds_read_b128 v[172:175], v167 offset:23552
	s_waitcnt lgkmcnt(1)
	v_mfma_f32_16x16x32_bf16 v[156:159], v[64:67], v[152:155], 0
	v_mfma_f32_16x16x32_bf16 v[152:155], v[68:71], v[152:155], 0
	s_waitcnt lgkmcnt(0)
	v_mfma_f32_16x16x32_bf16 v[156:159], v[60:63], v[172:175], v[156:159]
	v_mfma_f32_16x16x32_bf16 v[152:155], v[56:59], v[172:175], v[152:155]
	s_nop 6
	v_max3_f32 v32, v156, v157, v158
	v_max3_f32 v35, v159, v152, v153
	v_max3_f32 v32, v32, v154, v155
	v_max_f32_e32 v32, v32, v35
	v_add_f32_e32 v34, 0x41000000, v170
	v_cmp_gt_f32_e32 vcc, v32, v34
	s_cbranch_vccz .LBB0_394
	v_mov_b32_e32 v34, v32
	s_nop 1
	v_permlane16_swap_b32 v32, v34
	s_nop 0
	v_max_f32_e32 v34, v34, v34
	v_max_f32_e32 v32, v32, v32
	v_max_f32_e32 v32, v32, v34
	v_mov_b32_e32 v34, v32
	s_nop 1
	v_permlane32_swap_b32 v32, v34
	s_nop 0
	v_max3_f32 v34, v170, v32, v34
	v_sub_f32_e32 v32, v170, v34
	v_exp_f32_e32 v32, v32
	v_mov_b32_e32 v170, v34
	v_pk_mul_f32 v[126:127], v[126:127], v[32:33] op_sel_hi:[1,0]
	v_pk_mul_f32 v[124:125], v[124:125], v[32:33] op_sel_hi:[1,0]
	v_pk_mul_f32 v[122:123], v[122:123], v[32:33] op_sel_hi:[1,0]
	v_pk_mul_f32 v[120:121], v[120:121], v[32:33] op_sel_hi:[1,0]
	v_pk_mul_f32 v[118:119], v[118:119], v[32:33] op_sel_hi:[1,0]
	v_pk_mul_f32 v[116:117], v[116:117], v[32:33] op_sel_hi:[1,0]
	v_pk_mul_f32 v[114:115], v[114:115], v[32:33] op_sel_hi:[1,0]
	v_pk_mul_f32 v[112:113], v[112:113], v[32:33] op_sel_hi:[1,0]
	v_pk_mul_f32 v[130:131], v[130:131], v[32:33] op_sel_hi:[1,0]
	v_pk_mul_f32 v[128:129], v[128:129], v[32:33] op_sel_hi:[1,0]
.LBB0_394:
	v_pk_add_f32 v[154:155], v[154:155], v[170:171] op_sel_hi:[1,0] neg_lo:[0,1] neg_hi:[0,1]
	v_pk_add_f32 v[152:153], v[152:153], v[170:171] op_sel_hi:[1,0] neg_lo:[0,1] neg_hi:[0,1]
	v_pk_add_f32 v[156:157], v[156:157], v[170:171] op_sel_hi:[1,0] neg_lo:[0,1] neg_hi:[0,1]
	v_pk_add_f32 v[158:159], v[158:159], v[170:171] op_sel_hi:[1,0] neg_lo:[0,1] neg_hi:[0,1]
	v_exp_f32_e32 v154, v154
	v_exp_f32_e32 v155, v155
	v_exp_f32_e32 v152, v152
	v_exp_f32_e32 v153, v153
	v_exp_f32_e32 v156, v156
	v_exp_f32_e32 v157, v157
	v_exp_f32_e32 v158, v158
	v_exp_f32_e32 v159, v159
	v_cvt_pk_bf16_f32 v155, v154, v155
	v_cvt_pk_bf16_f32 v154, v152, v153
	v_cvt_pk_bf16_f32 v152, v156, v157
	v_cvt_pk_bf16_f32 v153, v158, v159
	s_nop 1
	v_mfma_f32_16x16x32_bf16 v[124:127], v[40:43], v[152:155], v[124:127]
	v_mfma_f32_16x16x32_bf16 v[120:123], v[44:47], v[152:155], v[120:123]
	v_mfma_f32_16x16x32_bf16 v[116:119], v[48:51], v[152:155], v[116:119]
	v_mfma_f32_16x16x32_bf16 v[112:115], v[52:55], v[152:155], v[112:115]
	v_mfma_f32_16x16x32_bf16 v[128:131], v[36:39], v[152:155], v[128:131]
	ds_read_b128 v[152:155], v167 offset:24576
	ds_read_b128 v[172:175], v167 offset:25600
	s_waitcnt lgkmcnt(1)
	v_mfma_f32_16x16x32_bf16 v[156:159], v[64:67], v[152:155], 0
	v_mfma_f32_16x16x32_bf16 v[152:155], v[68:71], v[152:155], 0
	s_waitcnt lgkmcnt(0)
	v_mfma_f32_16x16x32_bf16 v[156:159], v[60:63], v[172:175], v[156:159]
	v_mfma_f32_16x16x32_bf16 v[152:155], v[56:59], v[172:175], v[152:155]
	s_nop 6
	v_max3_f32 v32, v156, v157, v158
	v_max3_f32 v35, v159, v152, v153
	v_max3_f32 v32, v32, v154, v155
	v_max_f32_e32 v32, v32, v35
	v_add_f32_e32 v34, 0x41000000, v169
	v_cmp_gt_f32_e32 vcc, v32, v34
	s_cbranch_vccz .LBB0_396
	v_mov_b32_e32 v34, v32
	s_nop 1
	v_permlane16_swap_b32 v32, v34
	s_nop 0
	v_max_f32_e32 v34, v34, v34
	v_max_f32_e32 v32, v32, v32
	v_max_f32_e32 v32, v32, v34
	v_mov_b32_e32 v34, v32
	s_nop 1
	v_permlane32_swap_b32 v34, v32
	s_nop 0
	v_max3_f32 v34, v169, v34, v32
	v_sub_f32_e32 v32, v169, v34
	v_exp_f32_e32 v32, v32
	v_mov_b32_e32 v169, v34
	v_pk_mul_f32 v[106:107], v[106:107], v[32:33] op_sel_hi:[1,0]
	v_pk_mul_f32 v[104:105], v[104:105], v[32:33] op_sel_hi:[1,0]
	v_pk_mul_f32 v[102:103], v[102:103], v[32:33] op_sel_hi:[1,0]
	v_pk_mul_f32 v[100:101], v[100:101], v[32:33] op_sel_hi:[1,0]
	v_pk_mul_f32 v[98:99], v[98:99], v[32:33] op_sel_hi:[1,0]
	v_pk_mul_f32 v[96:97], v[96:97], v[32:33] op_sel_hi:[1,0]
	v_pk_mul_f32 v[94:95], v[94:95], v[32:33] op_sel_hi:[1,0]
	v_pk_mul_f32 v[92:93], v[92:93], v[32:33] op_sel_hi:[1,0]
	v_pk_mul_f32 v[110:111], v[110:111], v[32:33] op_sel_hi:[1,0]
	v_pk_mul_f32 v[108:109], v[108:109], v[32:33] op_sel_hi:[1,0]
.LBB0_396:
	v_pk_add_f32 v[154:155], v[154:155], v[168:169] op_sel:[0,1] op_sel_hi:[1,1] neg_lo:[0,1] neg_hi:[0,1]
	v_pk_add_f32 v[152:153], v[152:153], v[168:169] op_sel:[0,1] op_sel_hi:[1,1] neg_lo:[0,1] neg_hi:[0,1]
	v_pk_add_f32 v[156:157], v[156:157], v[168:169] op_sel:[0,1] op_sel_hi:[1,1] neg_lo:[0,1] neg_hi:[0,1]
	v_pk_add_f32 v[158:159], v[158:159], v[168:169] op_sel:[0,1] op_sel_hi:[1,1] neg_lo:[0,1] neg_hi:[0,1]
	v_exp_f32_e32 v154, v154
	v_exp_f32_e32 v155, v155
	v_exp_f32_e32 v152, v152
	v_exp_f32_e32 v153, v153
	v_exp_f32_e32 v156, v156
	v_exp_f32_e32 v157, v157
	v_exp_f32_e32 v158, v158
	v_exp_f32_e32 v159, v159
	v_cvt_pk_bf16_f32 v155, v154, v155
	v_cvt_pk_bf16_f32 v154, v152, v153
	v_cvt_pk_bf16_f32 v152, v156, v157
	v_cvt_pk_bf16_f32 v153, v158, v159
	s_nop 1
	v_mfma_f32_16x16x32_bf16 v[104:107], v[40:43], v[152:155], v[104:107]
	v_mfma_f32_16x16x32_bf16 v[100:103], v[44:47], v[152:155], v[100:103]
	v_mfma_f32_16x16x32_bf16 v[96:99], v[48:51], v[152:155], v[96:99]
	v_mfma_f32_16x16x32_bf16 v[92:95], v[52:55], v[152:155], v[92:95]
	v_mfma_f32_16x16x32_bf16 v[108:111], v[36:39], v[152:155], v[108:111]
	ds_read_b128 v[152:155], v167 offset:26624
	s_waitcnt lgkmcnt(0)
	v_mfma_f32_16x16x32_bf16 v[64:67], v[64:67], v[152:155], 0
	v_mfma_f32_16x16x32_bf16 v[68:71], v[68:71], v[152:155], 0
	ds_read_b128 v[152:155], v167 offset:27648
	s_waitcnt lgkmcnt(0)
	v_mfma_f32_16x16x32_bf16 v[60:63], v[60:63], v[152:155], v[64:67]
	v_mfma_f32_16x16x32_bf16 v[56:59], v[56:59], v[152:155], v[68:71]
	s_nop 6
	v_max3_f32 v32, v60, v61, v62
	v_max3_f32 v35, v63, v56, v57
	v_max3_f32 v32, v32, v58, v59
	v_max_f32_e32 v32, v32, v35
	v_add_f32_e32 v34, 0x41000000, v168
	v_cmp_gt_f32_e32 vcc, v32, v34
	s_cbranch_vccz .LBB0_381
	v_mov_b32_e32 v34, v32
	s_nop 1
	v_permlane16_swap_b32 v32, v34
	s_nop 0
	v_max_f32_e32 v34, v34, v34
	v_max_f32_e32 v32, v32, v32
	v_max_f32_e32 v32, v32, v34
	v_mov_b32_e32 v34, v32
	s_nop 1
	v_permlane32_swap_b32 v32, v34
	s_nop 0
	v_max3_f32 v34, v168, v32, v34
	v_sub_f32_e32 v32, v168, v34
	v_exp_f32_e32 v32, v32
	v_mov_b32_e32 v168, v34
	v_pk_mul_f32 v[86:87], v[86:87], v[32:33] op_sel_hi:[1,0]
	v_pk_mul_f32 v[84:85], v[84:85], v[32:33] op_sel_hi:[1,0]
	v_pk_mul_f32 v[82:83], v[82:83], v[32:33] op_sel_hi:[1,0]
	v_pk_mul_f32 v[80:81], v[80:81], v[32:33] op_sel_hi:[1,0]
	v_pk_mul_f32 v[78:79], v[78:79], v[32:33] op_sel_hi:[1,0]
	v_pk_mul_f32 v[76:77], v[76:77], v[32:33] op_sel_hi:[1,0]
	v_pk_mul_f32 v[74:75], v[74:75], v[32:33] op_sel_hi:[1,0]
	v_pk_mul_f32 v[72:73], v[72:73], v[32:33] op_sel_hi:[1,0]
	v_pk_mul_f32 v[90:91], v[90:91], v[32:33] op_sel_hi:[1,0]
	v_pk_mul_f32 v[88:89], v[88:89], v[32:33] op_sel_hi:[1,0]
	s_branch .LBB0_381
